# v24 plus GEMM K-loops: 44 v_lshl_add_u64 address computations folded into SADDR-form global_load_lds
# baseline (speedup 1.0000x reference)
; #define PG8_STAGE(bufoff, gbase, voff) do { _Pragma("unroll") for (int _i = 0; _i < 2; ++_i) \
;         __builtin_amdgcn_global_load_lds((const unsigned*)((const char*)(gbase) + (voff)[_i]), (PG8_LAS unsigned*)(lds + (bufoff) + ldsw + _i * 8192), 16, 0, 0); } while (0)
; #define PG8_LDA(dst, b, h) do { _Pragma("unroll") for (int m = 0; m < 4; ++m) _Pragma("unroll") for (int k = 0; k < 2; ++k) dst[m][k] = *(const PG8_LAS bf16x8*)(lds + PG8_SA(b, h) + aoff + m * 2048 + k * 1024); } while (0)
; #define PG8_LDB(dst, b, h) do { _Pragma("unroll") for (int n = 0; n < 2; ++n) _Pragma("unroll") for (int k = 0; k < 2; ++k) dst[n][k] = *(const PG8_LAS bf16x8*)(lds + PG8_SB(b, h) + boff + n * 2048 + k * 1024); } while (0)
; #define PG8_MMA(ai, bj, At, Bt) do { __builtin_amdgcn_s_setprio(1); _Pragma("unroll") for (int m = 0; m < 4; ++m) _Pragma("unroll") for (int n = 0; n < 2; ++n) _Pragma("unroll") for (int k = 0; k < 2; ++k) \
;         acc[ai][bj][m][n] = __builtin_amdgcn_mfma_f32_16x16x32_bf16(Bt[n][k], At[m][k], acc[ai][bj][m][n], 0, 0, 0); __builtin_amdgcn_s_setprio(0); } while (0)
; #define PG8_WAIT_V(n) asm volatile("s_waitcnt vmcnt(" #n ")" ::: "memory")
; #define PG8_WAIT_L(n) asm volatile("s_waitcnt lgkmcnt(" #n ")" ::: "memory")
; #define PG8_BAR __builtin_amdgcn_s_barrier()
; #define PG8_SCHED __builtin_amdgcn_sched_barrier(0)
; template <class Epi, class Sched, bool ALIGN_EPI = false, bool SP2 = false>
; __device__ __forceinline__ void gemm_phase(PG8_LAS unsigned char* lds, const Gemm g, const Sched& S, const Epi& E, int tid_in) {
;     ...
;             PG8_LDB(B0, 0, 0); PG8_LDB(B1, 0, 1); PG8_SCHED; PG8_LDA(At, 0, 0); PG8_STAGE(PG8_SA(1, 1), a1 + hstep, voffA);
;             PG8_WAIT_V(8); PG8_WAIT_L(0); PG8_BAR; PG8_MMA(0, 0, At, B0); PG8_MMA(0, 1, At, B1); PG8_BAR; PG8_SCHED;
;             PG8_LDA(At, 0, 1); PG8_STAGE(PG8_SB(0, 0), b2, voffB); PG8_STAGE(PG8_SB(0, 1), b2 + hstep, voffB); PG8_STAGE(PG8_SA(0, 0), a2, voffA);
;             PG8_WAIT_V(8); PG8_WAIT_L(0); PG8_BAR; PG8_MMA(1, 0, At, B0); PG8_MMA(1, 1, At, B1); PG8_BAR; PG8_SCHED;
.LBB0_296:
	s_add_u32 s20, s2, 0xfffc0080
	s_addc_u32 s21, s3, -1
	s_add_i32 s45, 0, 0x10000
	s_cmp_eq_u32 s44, 12
	s_cselect_b32 s23, s15, s21
	s_cselect_b32 s22, s40, s20
	s_cselect_b32 s21, s13, s43
	s_cselect_b32 s20, s41, s42
	s_add_i32 s48, 0, 0x14000
	v_add_u32_e32 v156, s45, v145
	v_add_u32_e32 v172, s48, v145
	ds_read_b128 v[140:143], v156
	ds_read_b128 v[148:151], v156 offset:1024
	ds_read_b128 v[152:155], v156 offset:2048
	ds_read_b128 v[156:159], v156 offset:3072
	ds_read_b128 v[160:163], v172
	ds_read_b128 v[164:167], v172 offset:1024
	ds_read_b128 v[168:171], v172 offset:2048
	ds_read_b128 v[172:175], v172 offset:3072
	s_add_i32 m0, s29, 0xc000
	ds_read_b128 v[176:179], v147
	ds_read_b128 v[180:183], v147 offset:1024
	ds_read_b128 v[184:187], v147 offset:2048
	ds_read_b128 v[188:191], v147 offset:3072
	ds_read_b128 v[204:207], v147 offset:4096
	ds_read_b128 v[208:211], v147 offset:5120
	ds_read_b128 v[212:215], v147 offset:6144
	ds_read_b128 v[216:219], v147 offset:7168
	global_load_lds_dwordx4 v136, s[2:3]
	s_add_i32 m0, s29, 0xe000
	s_nop 0
	global_load_lds_dwordx4 v138, s[2:3]
	s_waitcnt vmcnt(8)
	s_waitcnt lgkmcnt(0)
	s_barrier
	s_setprio 1
	s_waitcnt lgkmcnt(0)
	v_mfma_f32_16x16x32_bf16 v[126:129], v[140:143], v[176:179], v[126:129]
	v_mfma_f32_16x16x32_bf16 v[118:121], v[152:155], v[176:179], v[118:121]
	v_mfma_f32_16x16x32_bf16 v[110:113], v[140:143], v[184:187], v[110:113]
	v_mfma_f32_16x16x32_bf16 v[102:105], v[152:155], v[184:187], v[102:105]
	v_mfma_f32_16x16x32_bf16 v[94:97], v[140:143], v[204:207], v[94:97]
	v_mfma_f32_16x16x32_bf16 v[90:93], v[152:155], v[204:207], v[90:93]
	v_mfma_f32_16x16x32_bf16 v[78:81], v[140:143], v[212:215], v[78:81]
	v_mfma_f32_16x16x32_bf16 v[74:77], v[152:155], v[212:215], v[74:77]
	v_mfma_f32_16x16x32_bf16 v[126:129], v[148:151], v[180:183], v[126:129]
	v_mfma_f32_16x16x32_bf16 v[118:121], v[156:159], v[180:183], v[118:121]
	v_mfma_f32_16x16x32_bf16 v[110:113], v[148:151], v[188:191], v[110:113]
	v_mfma_f32_16x16x32_bf16 v[102:105], v[156:159], v[188:191], v[102:105]
	v_mfma_f32_16x16x32_bf16 v[94:97], v[148:151], v[208:211], v[94:97]
	v_mfma_f32_16x16x32_bf16 v[90:93], v[156:159], v[208:211], v[90:93]
	v_mfma_f32_16x16x32_bf16 v[78:81], v[148:151], v[216:219], v[78:81]
	v_mfma_f32_16x16x32_bf16 v[74:77], v[156:159], v[216:219], v[74:77]
	s_setprio 0
	s_setprio 1
	v_mfma_f32_16x16x32_bf16 v[122:125], v[160:163], v[176:179], v[122:125]
	v_mfma_f32_16x16x32_bf16 v[114:117], v[168:171], v[176:179], v[114:117]
	v_mfma_f32_16x16x32_bf16 v[106:109], v[160:163], v[184:187], v[106:109]
	v_mfma_f32_16x16x32_bf16 v[98:101], v[168:171], v[184:187], v[98:101]
	v_mfma_f32_16x16x32_bf16 v[86:89], v[160:163], v[204:207], v[86:89]
	v_mfma_f32_16x16x32_bf16 v[82:85], v[168:171], v[204:207], v[82:85]
	v_mfma_f32_16x16x32_bf16 v[70:73], v[160:163], v[212:215], v[70:73]
	v_mfma_f32_16x16x32_bf16 v[66:69], v[168:171], v[212:215], v[66:69]
	v_mfma_f32_16x16x32_bf16 v[122:125], v[164:167], v[180:183], v[122:125]
	v_mfma_f32_16x16x32_bf16 v[114:117], v[172:175], v[180:183], v[114:117]
	v_mfma_f32_16x16x32_bf16 v[106:109], v[164:167], v[188:191], v[106:109]
	v_mfma_f32_16x16x32_bf16 v[98:101], v[172:175], v[188:191], v[98:101]
	v_mfma_f32_16x16x32_bf16 v[86:89], v[164:167], v[208:211], v[86:89]
	v_mfma_f32_16x16x32_bf16 v[82:85], v[172:175], v[208:211], v[82:85]
	v_mfma_f32_16x16x32_bf16 v[70:73], v[164:167], v[216:219], v[70:73]
	v_mfma_f32_16x16x32_bf16 v[66:69], v[172:175], v[216:219], v[66:69]
	s_setprio 0
	s_barrier
	s_add_i32 s45, s45, s28
	v_lshl_add_u64 v[192:193], s[20:21], 0, v[32:33]
	s_mov_b32 m0, s45
	ds_read_b128 v[176:179], v147 offset:16384
	ds_read_b128 v[180:183], v147 offset:17408
	ds_read_b128 v[184:187], v147 offset:18432
	ds_read_b128 v[188:191], v147 offset:19456
	ds_read_b128 v[204:207], v147 offset:20480
	ds_read_b128 v[208:211], v147 offset:21504
	ds_read_b128 v[212:215], v147 offset:22528
	ds_read_b128 v[216:219], v147 offset:23552
	global_load_lds_dwordx4 v[192:193], off
	s_add_i32 m0, s45, 0x2000
	s_add_u32 s46, s20, 0x40000
	v_lshl_add_u64 v[220:221], s[20:21], 0, v[130:131]
	s_addc_u32 s47, s21, 0
	s_add_i32 s45, s48, s28
	global_load_lds_dwordx4 v[220:221], off
	s_mov_b32 m0, s45
	v_lshl_add_u64 v[224:225], s[22:23], 0, v[132:133]
	global_load_lds_dwordx4 v32, s[46:47]
	s_add_i32 m0, s45, 0x2000
	s_nop 0
	global_load_lds_dwordx4 v130, s[46:47]
	v_lshl_add_u64 v[222:223], s[22:23], 0, v[134:135]
	s_mov_b32 m0, s29
	s_nop 0
	global_load_lds_dwordx4 v[222:223], off
	s_mov_b32 m0, s30
	s_nop 0
	global_load_lds_dwordx4 v[224:225], off
	s_waitcnt vmcnt(8)
	s_waitcnt lgkmcnt(0)
	s_barrier
; #define PG8_STAGE(bufoff, gbase, voff) do { _Pragma("unroll") for (int _i = 0; _i < 2; ++_i) \
;         __builtin_amdgcn_global_load_lds((const unsigned*)((const char*)(gbase) + (voff)[_i]), (PG8_LAS unsigned*)(lds + (bufoff) + ldsw + _i * 8192), 16, 0, 0); } while (0)
; #define PG8_LDA(dst, b, h) do { _Pragma("unroll") for (int m = 0; m < 4; ++m) _Pragma("unroll") for (int k = 0; k < 2; ++k) dst[m][k] = *(const PG8_LAS bf16x8*)(lds + PG8_SA(b, h) + aoff + m * 2048 + k * 1024); } while (0)
; #define PG8_LDB(dst, b, h) do { _Pragma("unroll") for (int n = 0; n < 2; ++n) _Pragma("unroll") for (int k = 0; k < 2; ++k) dst[n][k] = *(const PG8_LAS bf16x8*)(lds + PG8_SB(b, h) + boff + n * 2048 + k * 1024); } while (0)
; #define PG8_MMA(ai, bj, At, Bt) do { __builtin_amdgcn_s_setprio(1); _Pragma("unroll") for (int m = 0; m < 4; ++m) _Pragma("unroll") for (int n = 0; n < 2; ++n) _Pragma("unroll") for (int k = 0; k < 2; ++k) \
;         acc[ai][bj][m][n] = __builtin_amdgcn_mfma_f32_16x16x32_bf16(Bt[n][k], At[m][k], acc[ai][bj][m][n], 0, 0, 0); __builtin_amdgcn_s_setprio(0); } while (0)
; #define PG8_WAIT_V(n) asm volatile("s_waitcnt vmcnt(" #n ")" ::: "memory")
; #define PG8_WAIT_L(n) asm volatile("s_waitcnt lgkmcnt(" #n ")" ::: "memory")
; #define PG8_BAR __builtin_amdgcn_s_barrier()
; #define PG8_SCHED __builtin_amdgcn_sched_barrier(0)
; template <class Epi, class Sched, bool ALIGN_EPI = false, bool SP2 = false>
; __device__ __forceinline__ void gemm_phase(PG8_LAS unsigned char* lds, const Gemm g, const Sched& S, const Epi& E, int tid_in) {
;     ...
;             PG8_WAIT_V(8); PG8_WAIT_L(0); PG8_BAR; PG8_MMA(1, 0, At, B0); PG8_MMA(1, 1, At, B1); PG8_BAR; PG8_SCHED;
;             PG8_LDB(B0, 1, 0); PG8_LDB(B1, 1, 1); PG8_SCHED; PG8_LDA(At, 1, 0); PG8_STAGE(PG8_SA(0, 1), a2 + hstep, voffA);
;             PG8_WAIT_V(8); PG8_WAIT_L(0); PG8_BAR; PG8_MMA(0, 0, At, B0); PG8_MMA(0, 1, At, B1); PG8_BAR; PG8_SCHED;
	s_setprio 1
	s_waitcnt lgkmcnt(0)
	v_mfma_f32_16x16x32_bf16 v[62:65], v[140:143], v[176:179], v[62:65]
	v_mfma_f32_16x16x32_bf16 v[58:61], v[152:155], v[176:179], v[58:61]
	v_mfma_f32_16x16x32_bf16 v[46:49], v[140:143], v[184:187], v[46:49]
	v_mfma_f32_16x16x32_bf16 v[42:45], v[152:155], v[184:187], v[42:45]
	v_mfma_f32_16x16x32_bf16 v[28:31], v[140:143], v[204:207], v[28:31]
	v_mfma_f32_16x16x32_bf16 v[24:27], v[152:155], v[204:207], v[24:27]
	v_mfma_f32_16x16x32_bf16 v[12:15], v[140:143], v[212:215], v[12:15]
	v_mfma_f32_16x16x32_bf16 v[8:11], v[152:155], v[212:215], v[8:11]
	v_mfma_f32_16x16x32_bf16 v[62:65], v[148:151], v[180:183], v[62:65]
	v_mfma_f32_16x16x32_bf16 v[58:61], v[156:159], v[180:183], v[58:61]
	v_mfma_f32_16x16x32_bf16 v[46:49], v[148:151], v[188:191], v[46:49]
	v_mfma_f32_16x16x32_bf16 v[42:45], v[156:159], v[188:191], v[42:45]
	v_mfma_f32_16x16x32_bf16 v[28:31], v[148:151], v[208:211], v[28:31]
	v_mfma_f32_16x16x32_bf16 v[24:27], v[156:159], v[208:211], v[24:27]
	v_mfma_f32_16x16x32_bf16 v[12:15], v[148:151], v[216:219], v[12:15]
	v_mfma_f32_16x16x32_bf16 v[8:11], v[156:159], v[216:219], v[8:11]
	s_setprio 0
	s_setprio 1
	v_mfma_f32_16x16x32_bf16 v[54:57], v[160:163], v[176:179], v[54:57]
	v_mfma_f32_16x16x32_bf16 v[50:53], v[168:171], v[176:179], v[50:53]
	v_mfma_f32_16x16x32_bf16 v[38:41], v[160:163], v[184:187], v[38:41]
	v_mfma_f32_16x16x32_bf16 v[34:37], v[168:171], v[184:187], v[34:37]
	v_mfma_f32_16x16x32_bf16 v[20:23], v[160:163], v[204:207], v[20:23]
	v_mfma_f32_16x16x32_bf16 v[16:19], v[168:171], v[204:207], v[16:19]
	v_mfma_f32_16x16x32_bf16 v[4:7], v[160:163], v[212:215], v[4:7]
	v_mfma_f32_16x16x32_bf16 v[0:3], v[168:171], v[212:215], v[0:3]
	v_mfma_f32_16x16x32_bf16 v[54:57], v[164:167], v[180:183], v[54:57]
	v_mfma_f32_16x16x32_bf16 v[50:53], v[172:175], v[180:183], v[50:53]
	v_mfma_f32_16x16x32_bf16 v[38:41], v[164:167], v[188:191], v[38:41]
	v_mfma_f32_16x16x32_bf16 v[34:37], v[172:175], v[188:191], v[34:37]
	v_mfma_f32_16x16x32_bf16 v[20:23], v[164:167], v[208:211], v[20:23]
	v_mfma_f32_16x16x32_bf16 v[16:19], v[172:175], v[208:211], v[16:19]
	v_mfma_f32_16x16x32_bf16 v[4:7], v[164:167], v[216:219], v[4:7]
	v_mfma_f32_16x16x32_bf16 v[0:3], v[172:175], v[216:219], v[0:3]
	s_setprio 0
	s_barrier
	s_add_i32 s45, 0, 0x18000
	s_add_i32 s46, 0, 0x1c000
	v_add_u32_e32 v156, s45, v145
	v_add_u32_e32 v172, s46, v145
	ds_read_b128 v[140:143], v156
	ds_read_b128 v[148:151], v156 offset:1024
	ds_read_b128 v[152:155], v156 offset:2048
	ds_read_b128 v[156:159], v156 offset:3072
	ds_read_b128 v[160:163], v172
	ds_read_b128 v[164:167], v172 offset:1024
	ds_read_b128 v[168:171], v172 offset:2048
	ds_read_b128 v[172:175], v172 offset:3072
	s_add_u32 s22, s22, 0x40000
	s_addc_u32 s23, s23, 0
	s_mov_b32 m0, s31
	ds_read_b128 v[176:179], v147 offset:32768
	ds_read_b128 v[180:183], v147 offset:33792
	ds_read_b128 v[184:187], v147 offset:34816
	ds_read_b128 v[188:191], v147 offset:35840
	ds_read_b128 v[204:207], v147 offset:36864
	ds_read_b128 v[208:211], v147 offset:37888
	ds_read_b128 v[212:215], v147 offset:38912
	ds_read_b128 v[216:219], v147 offset:39936
	global_load_lds_dwordx4 v134, s[22:23]
	s_mov_b32 m0, s34
	s_nop 0
	global_load_lds_dwordx4 v132, s[22:23]
	s_waitcnt vmcnt(8)
	s_waitcnt lgkmcnt(0)
	s_barrier
	s_setprio 1
	s_waitcnt lgkmcnt(0)
	v_mfma_f32_16x16x32_bf16 v[126:129], v[140:143], v[176:179], v[126:129]
	v_mfma_f32_16x16x32_bf16 v[118:121], v[152:155], v[176:179], v[118:121]
	v_mfma_f32_16x16x32_bf16 v[110:113], v[140:143], v[184:187], v[110:113]
	v_mfma_f32_16x16x32_bf16 v[102:105], v[152:155], v[184:187], v[102:105]
	v_mfma_f32_16x16x32_bf16 v[94:97], v[140:143], v[204:207], v[94:97]
	v_mfma_f32_16x16x32_bf16 v[90:93], v[152:155], v[204:207], v[90:93]
	v_mfma_f32_16x16x32_bf16 v[78:81], v[140:143], v[212:215], v[78:81]
	v_mfma_f32_16x16x32_bf16 v[74:77], v[152:155], v[212:215], v[74:77]
	v_mfma_f32_16x16x32_bf16 v[126:129], v[148:151], v[180:183], v[126:129]
	v_mfma_f32_16x16x32_bf16 v[118:121], v[156:159], v[180:183], v[118:121]
	v_mfma_f32_16x16x32_bf16 v[110:113], v[148:151], v[188:191], v[110:113]
	v_mfma_f32_16x16x32_bf16 v[102:105], v[156:159], v[188:191], v[102:105]
	v_mfma_f32_16x16x32_bf16 v[94:97], v[148:151], v[208:211], v[94:97]
	v_mfma_f32_16x16x32_bf16 v[90:93], v[156:159], v[208:211], v[90:93]
	v_mfma_f32_16x16x32_bf16 v[78:81], v[148:151], v[216:219], v[78:81]
	v_mfma_f32_16x16x32_bf16 v[74:77], v[156:159], v[216:219], v[74:77]
	s_setprio 0
	s_setprio 1
	v_mfma_f32_16x16x32_bf16 v[122:125], v[160:163], v[176:179], v[122:125]
	v_mfma_f32_16x16x32_bf16 v[114:117], v[168:171], v[176:179], v[114:117]
	v_mfma_f32_16x16x32_bf16 v[106:109], v[160:163], v[184:187], v[106:109]
	v_mfma_f32_16x16x32_bf16 v[98:101], v[168:171], v[184:187], v[98:101]
	v_mfma_f32_16x16x32_bf16 v[86:89], v[160:163], v[204:207], v[86:89]
	v_mfma_f32_16x16x32_bf16 v[82:85], v[168:171], v[204:207], v[82:85]
	v_mfma_f32_16x16x32_bf16 v[70:73], v[160:163], v[212:215], v[70:73]
	v_mfma_f32_16x16x32_bf16 v[66:69], v[168:171], v[212:215], v[66:69]
	v_mfma_f32_16x16x32_bf16 v[122:125], v[164:167], v[180:183], v[122:125]
	v_mfma_f32_16x16x32_bf16 v[114:117], v[172:175], v[180:183], v[114:117]
	v_mfma_f32_16x16x32_bf16 v[106:109], v[164:167], v[188:191], v[106:109]
	v_mfma_f32_16x16x32_bf16 v[98:101], v[172:175], v[188:191], v[98:101]
	v_mfma_f32_16x16x32_bf16 v[86:89], v[164:167], v[208:211], v[86:89]
	v_mfma_f32_16x16x32_bf16 v[82:85], v[172:175], v[208:211], v[82:85]
	v_mfma_f32_16x16x32_bf16 v[70:73], v[164:167], v[216:219], v[70:73]
	v_mfma_f32_16x16x32_bf16 v[66:69], v[172:175], v[216:219], v[66:69]
	s_setprio 0
	s_barrier
; #define PG8_STAGE(bufoff, gbase, voff) do { _Pragma("unroll") for (int _i = 0; _i < 2; ++_i) \
;         __builtin_amdgcn_global_load_lds((const unsigned*)((const char*)(gbase) + (voff)[_i]), (PG8_LAS unsigned*)(lds + (bufoff) + ldsw + _i * 8192), 16, 0, 0); } while (0)
; #define PG8_LDA(dst, b, h) do { _Pragma("unroll") for (int m = 0; m < 4; ++m) _Pragma("unroll") for (int k = 0; k < 2; ++k) dst[m][k] = *(const PG8_LAS bf16x8*)(lds + PG8_SA(b, h) + aoff + m * 2048 + k * 1024); } while (0)
; #define PG8_WAIT_V(n) asm volatile("s_waitcnt vmcnt(" #n ")" ::: "memory")
; #define PG8_WAIT_L(n) asm volatile("s_waitcnt lgkmcnt(" #n ")" ::: "memory")
; #define PG8_BAR __builtin_amdgcn_s_barrier()
; template <class Epi, class Sched, bool ALIGN_EPI = false, bool SP2 = false>
; __device__ __forceinline__ void gemm_phase(PG8_LAS unsigned char* lds, const Gemm g, const Sched& S, const Epi& E, int tid_in) {
;     ...
;         for (int t = 0; t < nt; t += 2) {
;             const bool last = (t == nt - 2);
;             const char* a1 = cA + (size_t)(t + 1) * kstep;
;             const char* a2 = last ? nA : cA + (size_t)(t + 2) * kstep; const char* b2 = last ? nB : cB + (size_t)(t + 2) * kstep;
;             const char* a3 = a2 + kstep; const char* b3 = b2 + kstep;
;             if (last && has_next) S.a_ready(nxt);
;             if constexpr (SP2) {
;             PG8_LDB(B0, 0, 0); PG8_LDB(B1, 0, 1); PG8_SCHED; PG8_LDA(At, 0, 0); PG8_STAGE(PG8_SA(1, 1), a1 + hstep, voffA);
;             PG8_WAIT_V(8); PG8_WAIT_L(0); PG8_BAR; PG8_MMA(0, 0, At, B0); PG8_MMA(0, 1, At, B1); PG8_BAR; PG8_SCHED;
;             PG8_LDA(At, 0, 1); PG8_STAGE(PG8_SB(0, 0), b2, voffB); PG8_STAGE(PG8_SB(0, 1), b2 + hstep, voffB); PG8_STAGE(PG8_SA(0, 0), a2, voffA);
;             PG8_WAIT_V(8); PG8_WAIT_L(0); PG8_BAR; PG8_MMA(1, 0, At, B0); PG8_MMA(1, 1, At, B1); PG8_BAR; PG8_SCHED;
;             PG8_LDB(B0, 1, 0); PG8_LDB(B1, 1, 1); PG8_SCHED; PG8_LDA(At, 1, 0); PG8_STAGE(PG8_SA(0, 1), a2 + hstep, voffA);
;             PG8_WAIT_V(8); PG8_WAIT_L(0); PG8_BAR; PG8_MMA(0, 0, At, B0); PG8_MMA(0, 1, At, B1); PG8_BAR; PG8_SCHED;
;             PG8_LDA(At, 1, 1); PG8_STAGE(PG8_SB(1, 0), b3, voffB); PG8_STAGE(PG8_SB(1, 1), b3 + hstep, voffB); PG8_STAGE(PG8_SA(1, 0), a3, voffA);
;             PG8_WAIT_V(8); PG8_WAIT_L(0); PG8_BAR; PG8_MMA(1, 0, At, B0); PG8_MMA(1, 1, At, B1); PG8_BAR; PG8_SCHED;
	s_add_i32 s22, s45, s28
	v_lshl_add_u64 v[192:193], v[192:193], 0, s[84:85]
	s_mov_b32 m0, s22
	ds_read_b128 v[176:179], v147 offset:49152
	ds_read_b128 v[180:183], v147 offset:50176
	ds_read_b128 v[184:187], v147 offset:51200
	ds_read_b128 v[188:191], v147 offset:52224
	ds_read_b128 v[204:207], v147 offset:53248
	ds_read_b128 v[208:211], v147 offset:54272
	ds_read_b128 v[212:215], v147 offset:55296
	ds_read_b128 v[216:219], v147 offset:56320
	global_load_lds_dwordx4 v[192:193], off
	s_add_i32 m0, s22, 0x2000
	s_add_u32 s20, s20, 0x40080
	v_lshl_add_u64 v[192:193], v[220:221], 0, s[84:85]
	s_addc_u32 s21, s21, 0
	s_add_i32 s22, s46, s28
	global_load_lds_dwordx4 v[192:193], off
	s_mov_b32 m0, s22
	s_nop 0
	global_load_lds_dwordx4 v32, s[20:21]
	s_add_i32 m0, s22, 0x2000
	s_nop 0
	global_load_lds_dwordx4 v130, s[20:21]
	v_lshl_add_u64 v[192:193], v[222:223], 0, s[84:85]
	s_mov_b32 m0, s35
	s_nop 0
	global_load_lds_dwordx4 v[192:193], off
	v_lshl_add_u64 v[192:193], v[224:225], 0, s[84:85]
	s_mov_b32 m0, s36
	s_nop 0
	global_load_lds_dwordx4 v[192:193], off
	s_waitcnt vmcnt(8)
	s_waitcnt lgkmcnt(0)
	s_barrier
	s_setprio 1
	s_waitcnt lgkmcnt(0)
	v_mfma_f32_16x16x32_bf16 v[62:65], v[140:143], v[176:179], v[62:65]
	v_mfma_f32_16x16x32_bf16 v[58:61], v[152:155], v[176:179], v[58:61]
	v_mfma_f32_16x16x32_bf16 v[46:49], v[140:143], v[184:187], v[46:49]
	v_mfma_f32_16x16x32_bf16 v[42:45], v[152:155], v[184:187], v[42:45]
	v_mfma_f32_16x16x32_bf16 v[28:31], v[140:143], v[204:207], v[28:31]
	v_mfma_f32_16x16x32_bf16 v[24:27], v[152:155], v[204:207], v[24:27]
	v_mfma_f32_16x16x32_bf16 v[12:15], v[140:143], v[212:215], v[12:15]
	v_mfma_f32_16x16x32_bf16 v[8:11], v[152:155], v[212:215], v[8:11]
	v_mfma_f32_16x16x32_bf16 v[62:65], v[148:151], v[180:183], v[62:65]
	v_mfma_f32_16x16x32_bf16 v[58:61], v[156:159], v[180:183], v[58:61]
	v_mfma_f32_16x16x32_bf16 v[46:49], v[148:151], v[188:191], v[46:49]
	v_mfma_f32_16x16x32_bf16 v[42:45], v[156:159], v[188:191], v[42:45]
	v_mfma_f32_16x16x32_bf16 v[28:31], v[148:151], v[208:211], v[28:31]
	v_mfma_f32_16x16x32_bf16 v[24:27], v[156:159], v[208:211], v[24:27]
	v_mfma_f32_16x16x32_bf16 v[12:15], v[148:151], v[216:219], v[12:15]
	v_mfma_f32_16x16x32_bf16 v[8:11], v[156:159], v[216:219], v[8:11]
	s_setprio 0
	s_setprio 1
	v_mfma_f32_16x16x32_bf16 v[54:57], v[160:163], v[176:179], v[54:57]
	v_mfma_f32_16x16x32_bf16 v[50:53], v[168:171], v[176:179], v[50:53]
	v_mfma_f32_16x16x32_bf16 v[38:41], v[160:163], v[184:187], v[38:41]
	v_mfma_f32_16x16x32_bf16 v[34:37], v[168:171], v[184:187], v[34:37]
	v_mfma_f32_16x16x32_bf16 v[20:23], v[160:163], v[204:207], v[20:23]
	v_mfma_f32_16x16x32_bf16 v[16:19], v[168:171], v[204:207], v[16:19]
	v_mfma_f32_16x16x32_bf16 v[4:7], v[160:163], v[212:215], v[4:7]
	v_mfma_f32_16x16x32_bf16 v[0:3], v[168:171], v[212:215], v[0:3]
	v_mfma_f32_16x16x32_bf16 v[54:57], v[164:167], v[180:183], v[54:57]
	v_mfma_f32_16x16x32_bf16 v[50:53], v[172:175], v[180:183], v[50:53]
	v_mfma_f32_16x16x32_bf16 v[38:41], v[164:167], v[188:191], v[38:41]
	v_mfma_f32_16x16x32_bf16 v[34:37], v[172:175], v[188:191], v[34:37]
	v_mfma_f32_16x16x32_bf16 v[20:23], v[164:167], v[208:211], v[20:23]
	v_mfma_f32_16x16x32_bf16 v[16:19], v[172:175], v[208:211], v[16:19]
	v_mfma_f32_16x16x32_bf16 v[4:7], v[164:167], v[216:219], v[4:7]
	v_mfma_f32_16x16x32_bf16 v[0:3], v[172:175], v[216:219], v[0:3]
	s_setprio 0
	s_barrier
	s_add_i32 s44, s44, 2
	s_add_u32 s2, s2, 0x100
	s_addc_u32 s3, s3, 0
	s_add_u32 s42, s42, 0x100
	s_addc_u32 s43, s43, 0
	s_cmp_gt_u32 s44, 13
	s_cbranch_scc0 .LBB0_296
	s_and_b64 vcc, exec, s[10:11]
	s_cbranch_vccz .LBB0_299
	s_barrier

; #define PG8_STAGE(bufoff, gbase, voff) do { _Pragma("unroll") for (int _i = 0; _i < 2; ++_i) \
;         __builtin_amdgcn_global_load_lds((const unsigned*)((const char*)(gbase) + (voff)[_i]), (PG8_LAS unsigned*)(lds + (bufoff) + ldsw + _i * 8192), 16, 0, 0); } while (0)
; #define PG8_LDA(dst, b, h) do { _Pragma("unroll") for (int m = 0; m < 4; ++m) _Pragma("unroll") for (int k = 0; k < 2; ++k) dst[m][k] = *(const PG8_LAS bf16x8*)(lds + PG8_SA(b, h) + aoff + m * 2048 + k * 1024); } while (0)
; #define PG8_LDB(dst, b, h) do { _Pragma("unroll") for (int n = 0; n < 2; ++n) _Pragma("unroll") for (int k = 0; k < 2; ++k) dst[n][k] = *(const PG8_LAS bf16x8*)(lds + PG8_SB(b, h) + boff + n * 2048 + k * 1024); } while (0)
; #define PG8_MMA(ai, bj, At, Bt) do { __builtin_amdgcn_s_setprio(1); _Pragma("unroll") for (int m = 0; m < 4; ++m) _Pragma("unroll") for (int n = 0; n < 2; ++n) _Pragma("unroll") for (int k = 0; k < 2; ++k) \
;         acc[ai][bj][m][n] = __builtin_amdgcn_mfma_f32_16x16x32_bf16(Bt[n][k], At[m][k], acc[ai][bj][m][n], 0, 0, 0); __builtin_amdgcn_s_setprio(0); } while (0)
; #define PG8_WAIT_V(n) asm volatile("s_waitcnt vmcnt(" #n ")" ::: "memory")
; #define PG8_WAIT_L(n) asm volatile("s_waitcnt lgkmcnt(" #n ")" ::: "memory")
; #define PG8_BAR __builtin_amdgcn_s_barrier()
; #define PG8_SCHED __builtin_amdgcn_sched_barrier(0)
; template <class Epi, class Sched, bool ALIGN_EPI = false, bool SP2 = false>
; __device__ __forceinline__ void gemm_phase(PG8_LAS unsigned char* lds, const Gemm g, const Sched& S, const Epi& E, int tid_in) {
;     ...
;             PG8_LDB(B0, 0, 0); PG8_LDB(B1, 0, 1); PG8_SCHED; PG8_LDA(At, 0, 0); PG8_STAGE(PG8_SA(1, 1), a1 + hstep, voffA);
;             PG8_WAIT_V(8); PG8_WAIT_L(0); PG8_BAR; PG8_MMA(0, 0, At, B0); PG8_MMA(0, 1, At, B1); PG8_BAR; PG8_SCHED;
;             PG8_LDA(At, 0, 1); PG8_STAGE(PG8_SB(0, 0), b2, voffB); PG8_STAGE(PG8_SB(0, 1), b2 + hstep, voffB); PG8_STAGE(PG8_SA(0, 0), a2, voffA);
;             PG8_WAIT_V(8); PG8_WAIT_L(0); PG8_BAR; PG8_MMA(1, 0, At, B0); PG8_MMA(1, 1, At, B1); PG8_BAR; PG8_SCHED;
.LBB0_340:
	s_add_u32 s24, s2, 0x100
	s_addc_u32 s25, s3, 0
	s_add_i32 s51, 0, 0x10000
	s_cmp_eq_u32 s50, 40
	s_cselect_b32 s29, s9, s25
	s_cselect_b32 s28, s8, s24
	s_cselect_b32 s27, s23, s49
	s_cselect_b32 s26, s22, s48
	s_add_i32 s53, 0, 0x14000
	v_add_u32_e32 v142, s51, v211
	v_add_u32_e32 v158, s53, v211
	ds_read_b128 v[130:133], v142
	ds_read_b128 v[134:137], v142 offset:1024
	ds_read_b128 v[138:141], v142 offset:2048
	ds_read_b128 v[142:145], v142 offset:3072
	ds_read_b128 v[146:149], v158
	ds_read_b128 v[150:153], v158 offset:1024
	ds_read_b128 v[154:157], v158 offset:2048
	ds_read_b128 v[158:161], v158 offset:3072
	v_lshl_add_u64 v[192:193], s[2:3], 0, v[184:185]
	s_add_i32 m0, s37, 0xc000
	ds_read_b128 v[162:165], v213
	ds_read_b128 v[166:169], v213 offset:1024
	ds_read_b128 v[170:173], v213 offset:2048
	ds_read_b128 v[174:177], v213 offset:3072
	ds_read_b128 v[188:191], v213 offset:4096
	ds_read_b128 v[204:207], v213 offset:5120
	ds_read_b128 v[214:217], v213 offset:6144
	ds_read_b128 v[218:221], v213 offset:7168
	global_load_lds_dwordx4 v[192:193], off
	v_lshl_add_u64 v[192:193], s[2:3], 0, v[186:187]
	s_add_i32 m0, s37, 0xe000
	s_nop 0
	global_load_lds_dwordx4 v[192:193], off
	s_waitcnt vmcnt(8)
	s_waitcnt lgkmcnt(0)
	s_barrier
	s_setprio 1
	s_waitcnt lgkmcnt(0)
	v_mfma_f32_16x16x32_bf16 v[126:129], v[130:133], v[162:165], v[126:129]
	v_mfma_f32_16x16x32_bf16 v[122:125], v[138:141], v[162:165], v[122:125]
	v_mfma_f32_16x16x32_bf16 v[110:113], v[130:133], v[170:173], v[110:113]
	v_mfma_f32_16x16x32_bf16 v[106:109], v[138:141], v[170:173], v[106:109]
	v_mfma_f32_16x16x32_bf16 v[94:97], v[130:133], v[188:191], v[94:97]
	v_mfma_f32_16x16x32_bf16 v[90:93], v[138:141], v[188:191], v[90:93]
	v_mfma_f32_16x16x32_bf16 v[78:81], v[130:133], v[214:217], v[78:81]
	v_mfma_f32_16x16x32_bf16 v[74:77], v[138:141], v[214:217], v[74:77]
	v_mfma_f32_16x16x32_bf16 v[126:129], v[134:137], v[166:169], v[126:129]
	v_mfma_f32_16x16x32_bf16 v[122:125], v[142:145], v[166:169], v[122:125]
	v_mfma_f32_16x16x32_bf16 v[110:113], v[134:137], v[174:177], v[110:113]
	v_mfma_f32_16x16x32_bf16 v[106:109], v[142:145], v[174:177], v[106:109]
	v_mfma_f32_16x16x32_bf16 v[94:97], v[134:137], v[204:207], v[94:97]
	v_mfma_f32_16x16x32_bf16 v[90:93], v[142:145], v[204:207], v[90:93]
	v_mfma_f32_16x16x32_bf16 v[78:81], v[134:137], v[218:221], v[78:81]
	v_mfma_f32_16x16x32_bf16 v[74:77], v[142:145], v[218:221], v[74:77]
	s_setprio 0
	s_setprio 1
	v_mfma_f32_16x16x32_bf16 v[118:121], v[146:149], v[162:165], v[118:121]
	v_mfma_f32_16x16x32_bf16 v[114:117], v[154:157], v[162:165], v[114:117]
	v_mfma_f32_16x16x32_bf16 v[102:105], v[146:149], v[170:173], v[102:105]
	v_mfma_f32_16x16x32_bf16 v[98:101], v[154:157], v[170:173], v[98:101]
	v_mfma_f32_16x16x32_bf16 v[86:89], v[146:149], v[188:191], v[86:89]
	v_mfma_f32_16x16x32_bf16 v[82:85], v[154:157], v[188:191], v[82:85]
	v_mfma_f32_16x16x32_bf16 v[70:73], v[146:149], v[214:217], v[70:73]
	v_mfma_f32_16x16x32_bf16 v[66:69], v[154:157], v[214:217], v[66:69]
	v_mfma_f32_16x16x32_bf16 v[118:121], v[150:153], v[166:169], v[118:121]
	v_mfma_f32_16x16x32_bf16 v[114:117], v[158:161], v[166:169], v[114:117]
	v_mfma_f32_16x16x32_bf16 v[102:105], v[150:153], v[174:177], v[102:105]
	v_mfma_f32_16x16x32_bf16 v[98:101], v[158:161], v[174:177], v[98:101]
	v_mfma_f32_16x16x32_bf16 v[86:89], v[150:153], v[204:207], v[86:89]
	v_mfma_f32_16x16x32_bf16 v[82:85], v[158:161], v[204:207], v[82:85]
	v_mfma_f32_16x16x32_bf16 v[70:73], v[150:153], v[218:221], v[70:73]
	v_mfma_f32_16x16x32_bf16 v[66:69], v[158:161], v[218:221], v[66:69]
	s_setprio 0
	s_barrier
	s_add_i32 s2, s51, s36
	v_lshl_add_u64 v[192:193], s[26:27], 0, v[32:33]
	s_mov_b32 m0, s2
	ds_read_b128 v[162:165], v213 offset:16384
	ds_read_b128 v[166:169], v213 offset:17408
	ds_read_b128 v[170:173], v213 offset:18432
	ds_read_b128 v[174:177], v213 offset:19456
	ds_read_b128 v[188:191], v213 offset:20480
	ds_read_b128 v[204:207], v213 offset:21504
	ds_read_b128 v[214:217], v213 offset:22528
	ds_read_b128 v[218:221], v213 offset:23552
	global_load_lds_dwordx4 v[192:193], off
	s_add_i32 m0, s2, 0x2000
	s_add_u32 s2, s26, 0xb0000
	v_lshl_add_u64 v[208:209], s[26:27], 0, v[178:179]
	s_addc_u32 s3, s27, 0
	s_add_i32 s51, s53, s36
	global_load_lds_dwordx4 v[208:209], off
	s_mov_b32 m0, s51
	v_lshl_add_u64 v[224:225], s[28:29], 0, v[180:181]
	global_load_lds_dwordx4 v32, s[2:3]
	s_add_i32 m0, s51, 0x2000
	s_nop 0
	global_load_lds_dwordx4 v178, s[2:3]
	v_lshl_add_u64 v[222:223], s[28:29], 0, v[182:183]
	s_mov_b32 m0, s37
	s_nop 0
	global_load_lds_dwordx4 v[222:223], off
	s_mov_b32 m0, s38
	s_nop 0
	global_load_lds_dwordx4 v[224:225], off
	s_waitcnt vmcnt(8)
	s_waitcnt lgkmcnt(0)
	s_barrier
; #define PG8_STAGE(bufoff, gbase, voff) do { _Pragma("unroll") for (int _i = 0; _i < 2; ++_i) \
;         __builtin_amdgcn_global_load_lds((const unsigned*)((const char*)(gbase) + (voff)[_i]), (PG8_LAS unsigned*)(lds + (bufoff) + ldsw + _i * 8192), 16, 0, 0); } while (0)
; #define PG8_LDA(dst, b, h) do { _Pragma("unroll") for (int m = 0; m < 4; ++m) _Pragma("unroll") for (int k = 0; k < 2; ++k) dst[m][k] = *(const PG8_LAS bf16x8*)(lds + PG8_SA(b, h) + aoff + m * 2048 + k * 1024); } while (0)
; #define PG8_LDB(dst, b, h) do { _Pragma("unroll") for (int n = 0; n < 2; ++n) _Pragma("unroll") for (int k = 0; k < 2; ++k) dst[n][k] = *(const PG8_LAS bf16x8*)(lds + PG8_SB(b, h) + boff + n * 2048 + k * 1024); } while (0)
; #define PG8_MMA(ai, bj, At, Bt) do { __builtin_amdgcn_s_setprio(1); _Pragma("unroll") for (int m = 0; m < 4; ++m) _Pragma("unroll") for (int n = 0; n < 2; ++n) _Pragma("unroll") for (int k = 0; k < 2; ++k) \
;         acc[ai][bj][m][n] = __builtin_amdgcn_mfma_f32_16x16x32_bf16(Bt[n][k], At[m][k], acc[ai][bj][m][n], 0, 0, 0); __builtin_amdgcn_s_setprio(0); } while (0)
; #define PG8_WAIT_V(n) asm volatile("s_waitcnt vmcnt(" #n ")" ::: "memory")
; #define PG8_WAIT_L(n) asm volatile("s_waitcnt lgkmcnt(" #n ")" ::: "memory")
; #define PG8_BAR __builtin_amdgcn_s_barrier()
; #define PG8_SCHED __builtin_amdgcn_sched_barrier(0)
; template <class Epi, class Sched, bool ALIGN_EPI = false, bool SP2 = false>
; __device__ __forceinline__ void gemm_phase(PG8_LAS unsigned char* lds, const Gemm g, const Sched& S, const Epi& E, int tid_in) {
;     ...
;             PG8_WAIT_V(8); PG8_WAIT_L(0); PG8_BAR; PG8_MMA(1, 0, At, B0); PG8_MMA(1, 1, At, B1); PG8_BAR; PG8_SCHED;
;             PG8_LDB(B0, 1, 0); PG8_LDB(B1, 1, 1); PG8_SCHED; PG8_LDA(At, 1, 0); PG8_STAGE(PG8_SA(0, 1), a2 + hstep, voffA);
;             PG8_WAIT_V(8); PG8_WAIT_L(0); PG8_BAR; PG8_MMA(0, 0, At, B0); PG8_MMA(0, 1, At, B1); PG8_BAR; PG8_SCHED;
	s_setprio 1
	s_waitcnt lgkmcnt(0)
	v_mfma_f32_16x16x32_bf16 v[62:65], v[130:133], v[162:165], v[62:65]
	v_mfma_f32_16x16x32_bf16 v[58:61], v[138:141], v[162:165], v[58:61]
	v_mfma_f32_16x16x32_bf16 v[46:49], v[130:133], v[170:173], v[46:49]
	v_mfma_f32_16x16x32_bf16 v[42:45], v[138:141], v[170:173], v[42:45]
	v_mfma_f32_16x16x32_bf16 v[28:31], v[130:133], v[188:191], v[28:31]
	v_mfma_f32_16x16x32_bf16 v[24:27], v[138:141], v[188:191], v[24:27]
	v_mfma_f32_16x16x32_bf16 v[12:15], v[130:133], v[214:217], v[12:15]
	v_mfma_f32_16x16x32_bf16 v[8:11], v[138:141], v[214:217], v[8:11]
	v_mfma_f32_16x16x32_bf16 v[62:65], v[134:137], v[166:169], v[62:65]
	v_mfma_f32_16x16x32_bf16 v[58:61], v[142:145], v[166:169], v[58:61]
	v_mfma_f32_16x16x32_bf16 v[46:49], v[134:137], v[174:177], v[46:49]
	v_mfma_f32_16x16x32_bf16 v[42:45], v[142:145], v[174:177], v[42:45]
	v_mfma_f32_16x16x32_bf16 v[28:31], v[134:137], v[204:207], v[28:31]
	v_mfma_f32_16x16x32_bf16 v[24:27], v[142:145], v[204:207], v[24:27]
	v_mfma_f32_16x16x32_bf16 v[12:15], v[134:137], v[218:221], v[12:15]
	v_mfma_f32_16x16x32_bf16 v[8:11], v[142:145], v[218:221], v[8:11]
	s_setprio 0
	s_setprio 1
	v_mfma_f32_16x16x32_bf16 v[54:57], v[146:149], v[162:165], v[54:57]
	v_mfma_f32_16x16x32_bf16 v[50:53], v[154:157], v[162:165], v[50:53]
	v_mfma_f32_16x16x32_bf16 v[38:41], v[146:149], v[170:173], v[38:41]
	v_mfma_f32_16x16x32_bf16 v[34:37], v[154:157], v[170:173], v[34:37]
	v_mfma_f32_16x16x32_bf16 v[20:23], v[146:149], v[188:191], v[20:23]
	v_mfma_f32_16x16x32_bf16 v[16:19], v[154:157], v[188:191], v[16:19]
	v_mfma_f32_16x16x32_bf16 v[4:7], v[146:149], v[214:217], v[4:7]
	v_mfma_f32_16x16x32_bf16 v[0:3], v[154:157], v[214:217], v[0:3]
	v_mfma_f32_16x16x32_bf16 v[54:57], v[150:153], v[166:169], v[54:57]
	v_mfma_f32_16x16x32_bf16 v[50:53], v[158:161], v[166:169], v[50:53]
	v_mfma_f32_16x16x32_bf16 v[38:41], v[150:153], v[174:177], v[38:41]
	v_mfma_f32_16x16x32_bf16 v[34:37], v[158:161], v[174:177], v[34:37]
	v_mfma_f32_16x16x32_bf16 v[20:23], v[150:153], v[204:207], v[20:23]
	v_mfma_f32_16x16x32_bf16 v[16:19], v[158:161], v[204:207], v[16:19]
	v_mfma_f32_16x16x32_bf16 v[4:7], v[150:153], v[218:221], v[4:7]
	v_mfma_f32_16x16x32_bf16 v[0:3], v[158:161], v[218:221], v[0:3]
	s_setprio 0
	s_barrier
	s_add_i32 s51, 0, 0x18000
	s_add_i32 s53, 0, 0x1c000
	v_add_u32_e32 v142, s51, v211
	v_add_u32_e32 v158, s53, v211
	ds_read_b128 v[130:133], v142
	ds_read_b128 v[134:137], v142 offset:1024
	ds_read_b128 v[138:141], v142 offset:2048
	ds_read_b128 v[142:145], v142 offset:3072
	ds_read_b128 v[146:149], v158
	ds_read_b128 v[150:153], v158 offset:1024
	ds_read_b128 v[154:157], v158 offset:2048
	ds_read_b128 v[158:161], v158 offset:3072
	s_add_u32 s2, s28, 0xb0000
	s_addc_u32 s3, s29, 0
	s_mov_b32 m0, s39
	ds_read_b128 v[162:165], v213 offset:32768
	ds_read_b128 v[166:169], v213 offset:33792
	ds_read_b128 v[170:173], v213 offset:34816
	ds_read_b128 v[174:177], v213 offset:35840
	ds_read_b128 v[188:191], v213 offset:36864
	ds_read_b128 v[204:207], v213 offset:37888
	ds_read_b128 v[214:217], v213 offset:38912
	ds_read_b128 v[218:221], v213 offset:39936
	global_load_lds_dwordx4 v182, s[2:3]
	s_mov_b32 m0, s40
	s_nop 0
	global_load_lds_dwordx4 v180, s[2:3]
	s_waitcnt vmcnt(8)
	s_waitcnt lgkmcnt(0)
	s_barrier
	s_setprio 1
	s_waitcnt lgkmcnt(0)
	v_mfma_f32_16x16x32_bf16 v[126:129], v[130:133], v[162:165], v[126:129]
	v_mfma_f32_16x16x32_bf16 v[122:125], v[138:141], v[162:165], v[122:125]
	v_mfma_f32_16x16x32_bf16 v[110:113], v[130:133], v[170:173], v[110:113]
	v_mfma_f32_16x16x32_bf16 v[106:109], v[138:141], v[170:173], v[106:109]
	v_mfma_f32_16x16x32_bf16 v[94:97], v[130:133], v[188:191], v[94:97]
	v_mfma_f32_16x16x32_bf16 v[90:93], v[138:141], v[188:191], v[90:93]
	v_mfma_f32_16x16x32_bf16 v[78:81], v[130:133], v[214:217], v[78:81]
	v_mfma_f32_16x16x32_bf16 v[74:77], v[138:141], v[214:217], v[74:77]
	v_mfma_f32_16x16x32_bf16 v[126:129], v[134:137], v[166:169], v[126:129]
	v_mfma_f32_16x16x32_bf16 v[122:125], v[142:145], v[166:169], v[122:125]
	v_mfma_f32_16x16x32_bf16 v[110:113], v[134:137], v[174:177], v[110:113]
	v_mfma_f32_16x16x32_bf16 v[106:109], v[142:145], v[174:177], v[106:109]
	v_mfma_f32_16x16x32_bf16 v[94:97], v[134:137], v[204:207], v[94:97]
	v_mfma_f32_16x16x32_bf16 v[90:93], v[142:145], v[204:207], v[90:93]
	v_mfma_f32_16x16x32_bf16 v[78:81], v[134:137], v[218:221], v[78:81]
	v_mfma_f32_16x16x32_bf16 v[74:77], v[142:145], v[218:221], v[74:77]
	s_setprio 0
	s_setprio 1
	v_mfma_f32_16x16x32_bf16 v[118:121], v[146:149], v[162:165], v[118:121]
	v_mfma_f32_16x16x32_bf16 v[114:117], v[154:157], v[162:165], v[114:117]
	v_mfma_f32_16x16x32_bf16 v[102:105], v[146:149], v[170:173], v[102:105]
	v_mfma_f32_16x16x32_bf16 v[98:101], v[154:157], v[170:173], v[98:101]
	v_mfma_f32_16x16x32_bf16 v[86:89], v[146:149], v[188:191], v[86:89]
	v_mfma_f32_16x16x32_bf16 v[82:85], v[154:157], v[188:191], v[82:85]
	v_mfma_f32_16x16x32_bf16 v[70:73], v[146:149], v[214:217], v[70:73]
	v_mfma_f32_16x16x32_bf16 v[66:69], v[154:157], v[214:217], v[66:69]
	v_mfma_f32_16x16x32_bf16 v[118:121], v[150:153], v[166:169], v[118:121]
	v_mfma_f32_16x16x32_bf16 v[114:117], v[158:161], v[166:169], v[114:117]
	v_mfma_f32_16x16x32_bf16 v[102:105], v[150:153], v[174:177], v[102:105]
	v_mfma_f32_16x16x32_bf16 v[98:101], v[158:161], v[174:177], v[98:101]
	v_mfma_f32_16x16x32_bf16 v[86:89], v[150:153], v[204:207], v[86:89]
	v_mfma_f32_16x16x32_bf16 v[82:85], v[158:161], v[204:207], v[82:85]
	v_mfma_f32_16x16x32_bf16 v[70:73], v[150:153], v[218:221], v[70:73]
	v_mfma_f32_16x16x32_bf16 v[66:69], v[158:161], v[218:221], v[66:69]
	s_setprio 0
	s_barrier
; #define PG8_STAGE(bufoff, gbase, voff) do { _Pragma("unroll") for (int _i = 0; _i < 2; ++_i) \
;         __builtin_amdgcn_global_load_lds((const unsigned*)((const char*)(gbase) + (voff)[_i]), (PG8_LAS unsigned*)(lds + (bufoff) + ldsw + _i * 8192), 16, 0, 0); } while (0)
; #define PG8_LDA(dst, b, h) do { _Pragma("unroll") for (int m = 0; m < 4; ++m) _Pragma("unroll") for (int k = 0; k < 2; ++k) dst[m][k] = *(const PG8_LAS bf16x8*)(lds + PG8_SA(b, h) + aoff + m * 2048 + k * 1024); } while (0)
; #define PG8_WAIT_V(n) asm volatile("s_waitcnt vmcnt(" #n ")" ::: "memory")
; #define PG8_WAIT_L(n) asm volatile("s_waitcnt lgkmcnt(" #n ")" ::: "memory")
; #define PG8_BAR __builtin_amdgcn_s_barrier()
; template <class Epi, class Sched, bool ALIGN_EPI = false, bool SP2 = false>
; __device__ __forceinline__ void gemm_phase(PG8_LAS unsigned char* lds, const Gemm g, const Sched& S, const Epi& E, int tid_in) {
;     ...
;         for (int t = 0; t < nt; t += 2) {
;             const bool last = (t == nt - 2);
;             const char* a1 = cA + (size_t)(t + 1) * kstep;
;             const char* a2 = last ? nA : cA + (size_t)(t + 2) * kstep; const char* b2 = last ? nB : cB + (size_t)(t + 2) * kstep;
;             const char* a3 = a2 + kstep; const char* b3 = b2 + kstep;
;             if (last && has_next) S.a_ready(nxt);
;             if constexpr (SP2) {
;             PG8_LDB(B0, 0, 0); PG8_LDB(B1, 0, 1); PG8_SCHED; PG8_LDA(At, 0, 0); PG8_STAGE(PG8_SA(1, 1), a1 + hstep, voffA);
;             PG8_WAIT_V(8); PG8_WAIT_L(0); PG8_BAR; PG8_MMA(0, 0, At, B0); PG8_MMA(0, 1, At, B1); PG8_BAR; PG8_SCHED;
;             PG8_LDA(At, 0, 1); PG8_STAGE(PG8_SB(0, 0), b2, voffB); PG8_STAGE(PG8_SB(0, 1), b2 + hstep, voffB); PG8_STAGE(PG8_SA(0, 0), a2, voffA);
;             PG8_WAIT_V(8); PG8_WAIT_L(0); PG8_BAR; PG8_MMA(1, 0, At, B0); PG8_MMA(1, 1, At, B1); PG8_BAR; PG8_SCHED;
;             PG8_LDB(B0, 1, 0); PG8_LDB(B1, 1, 1); PG8_SCHED; PG8_LDA(At, 1, 0); PG8_STAGE(PG8_SA(0, 1), a2 + hstep, voffA);
;             PG8_WAIT_V(8); PG8_WAIT_L(0); PG8_BAR; PG8_MMA(0, 0, At, B0); PG8_MMA(0, 1, At, B1); PG8_BAR; PG8_SCHED;
;             PG8_LDA(At, 1, 1); PG8_STAGE(PG8_SB(1, 0), b3, voffB); PG8_STAGE(PG8_SB(1, 1), b3 + hstep, voffB); PG8_STAGE(PG8_SA(1, 0), a3, voffA);
;             PG8_WAIT_V(8); PG8_WAIT_L(0); PG8_BAR; PG8_MMA(1, 0, At, B0); PG8_MMA(1, 1, At, B1); PG8_BAR; PG8_SCHED;
	s_add_i32 s2, s51, s36
	v_lshl_add_u64 v[192:193], v[192:193], 0, s[84:85]
	s_mov_b32 m0, s2
	ds_read_b128 v[162:165], v213 offset:49152
	ds_read_b128 v[166:169], v213 offset:50176
	ds_read_b128 v[170:173], v213 offset:51200
	ds_read_b128 v[174:177], v213 offset:52224
	ds_read_b128 v[188:191], v213 offset:53248
	ds_read_b128 v[204:207], v213 offset:54272
	ds_read_b128 v[214:217], v213 offset:55296
	ds_read_b128 v[218:221], v213 offset:56320
	global_load_lds_dwordx4 v[192:193], off
	s_add_i32 m0, s2, 0x2000
	s_add_u32 s2, s26, 0xb0080
	v_lshl_add_u64 v[192:193], v[208:209], 0, s[84:85]
	s_addc_u32 s3, s27, 0
	s_add_i32 s26, s53, s36
	global_load_lds_dwordx4 v[192:193], off
	s_mov_b32 m0, s26
	s_nop 0
	global_load_lds_dwordx4 v32, s[2:3]
	s_add_i32 m0, s26, 0x2000
	s_nop 0
	global_load_lds_dwordx4 v178, s[2:3]
	v_lshl_add_u64 v[192:193], v[222:223], 0, s[84:85]
	s_mov_b32 m0, s41
	s_nop 0
	global_load_lds_dwordx4 v[192:193], off
	v_lshl_add_u64 v[192:193], v[224:225], 0, s[84:85]
	s_mov_b32 m0, s42
	s_nop 0
	global_load_lds_dwordx4 v[192:193], off
	s_waitcnt vmcnt(8)
	s_waitcnt lgkmcnt(0)
	s_barrier
	s_setprio 1
	s_waitcnt lgkmcnt(0)
	v_mfma_f32_16x16x32_bf16 v[62:65], v[130:133], v[162:165], v[62:65]
	v_mfma_f32_16x16x32_bf16 v[58:61], v[138:141], v[162:165], v[58:61]
	v_mfma_f32_16x16x32_bf16 v[46:49], v[130:133], v[170:173], v[46:49]
	v_mfma_f32_16x16x32_bf16 v[42:45], v[138:141], v[170:173], v[42:45]
	v_mfma_f32_16x16x32_bf16 v[28:31], v[130:133], v[188:191], v[28:31]
	v_mfma_f32_16x16x32_bf16 v[24:27], v[138:141], v[188:191], v[24:27]
	v_mfma_f32_16x16x32_bf16 v[12:15], v[130:133], v[214:217], v[12:15]
	v_mfma_f32_16x16x32_bf16 v[8:11], v[138:141], v[214:217], v[8:11]
	v_mfma_f32_16x16x32_bf16 v[62:65], v[134:137], v[166:169], v[62:65]
	v_mfma_f32_16x16x32_bf16 v[58:61], v[142:145], v[166:169], v[58:61]
	v_mfma_f32_16x16x32_bf16 v[46:49], v[134:137], v[174:177], v[46:49]
	v_mfma_f32_16x16x32_bf16 v[42:45], v[142:145], v[174:177], v[42:45]
	v_mfma_f32_16x16x32_bf16 v[28:31], v[134:137], v[204:207], v[28:31]
	v_mfma_f32_16x16x32_bf16 v[24:27], v[142:145], v[204:207], v[24:27]
	v_mfma_f32_16x16x32_bf16 v[12:15], v[134:137], v[218:221], v[12:15]
	v_mfma_f32_16x16x32_bf16 v[8:11], v[142:145], v[218:221], v[8:11]
	s_setprio 0
	s_setprio 1
	v_mfma_f32_16x16x32_bf16 v[54:57], v[146:149], v[162:165], v[54:57]
	v_mfma_f32_16x16x32_bf16 v[50:53], v[154:157], v[162:165], v[50:53]
	v_mfma_f32_16x16x32_bf16 v[38:41], v[146:149], v[170:173], v[38:41]
	v_mfma_f32_16x16x32_bf16 v[34:37], v[154:157], v[170:173], v[34:37]
	v_mfma_f32_16x16x32_bf16 v[20:23], v[146:149], v[188:191], v[20:23]
	v_mfma_f32_16x16x32_bf16 v[16:19], v[154:157], v[188:191], v[16:19]
	v_mfma_f32_16x16x32_bf16 v[4:7], v[146:149], v[214:217], v[4:7]
	v_mfma_f32_16x16x32_bf16 v[0:3], v[154:157], v[214:217], v[0:3]
	v_mfma_f32_16x16x32_bf16 v[54:57], v[150:153], v[166:169], v[54:57]
	v_mfma_f32_16x16x32_bf16 v[50:53], v[158:161], v[166:169], v[50:53]
	v_mfma_f32_16x16x32_bf16 v[38:41], v[150:153], v[174:177], v[38:41]
	v_mfma_f32_16x16x32_bf16 v[34:37], v[158:161], v[174:177], v[34:37]
	v_mfma_f32_16x16x32_bf16 v[20:23], v[150:153], v[204:207], v[20:23]
	v_mfma_f32_16x16x32_bf16 v[16:19], v[158:161], v[204:207], v[16:19]
	v_mfma_f32_16x16x32_bf16 v[4:7], v[150:153], v[218:221], v[4:7]
	v_mfma_f32_16x16x32_bf16 v[0:3], v[158:161], v[218:221], v[0:3]
	s_setprio 0
	s_barrier
	s_add_i32 s50, s50, 2
	s_add_u32 s48, s48, 0x100
	s_addc_u32 s49, s49, 0
	s_cmp_gt_u32 s50, 41
	s_mov_b64 s[2:3], s[24:25]
	s_cbranch_scc0 .LBB0_340
	s_and_b64 vcc, exec, s[20:21]
	s_cbranch_vccz .LBB0_343
	s_barrier

; #define PG8_STAGE(bufoff, gbase, voff) do { _Pragma("unroll") for (int _i = 0; _i < 2; ++_i) \
;         __builtin_amdgcn_global_load_lds((const unsigned*)((const char*)(gbase) + (voff)[_i]), (PG8_LAS unsigned*)(lds + (bufoff) + ldsw + _i * 8192), 16, 0, 0); } while (0)
; #define PG8_LDA(dst, b, h) do { _Pragma("unroll") for (int m = 0; m < 4; ++m) _Pragma("unroll") for (int k = 0; k < 2; ++k) dst[m][k] = *(const PG8_LAS bf16x8*)(lds + PG8_SA(b, h) + aoff + m * 2048 + k * 1024); } while (0)
; #define PG8_LDB(dst, b, h) do { _Pragma("unroll") for (int n = 0; n < 2; ++n) _Pragma("unroll") for (int k = 0; k < 2; ++k) dst[n][k] = *(const PG8_LAS bf16x8*)(lds + PG8_SB(b, h) + boff + n * 2048 + k * 1024); } while (0)
; #define PG8_MMA(ai, bj, At, Bt) do { __builtin_amdgcn_s_setprio(1); _Pragma("unroll") for (int m = 0; m < 4; ++m) _Pragma("unroll") for (int n = 0; n < 2; ++n) _Pragma("unroll") for (int k = 0; k < 2; ++k) \
;         acc[ai][bj][m][n] = __builtin_amdgcn_mfma_f32_16x16x32_bf16(Bt[n][k], At[m][k], acc[ai][bj][m][n], 0, 0, 0); __builtin_amdgcn_s_setprio(0); } while (0)
; #define PG8_WAIT_V(n) asm volatile("s_waitcnt vmcnt(" #n ")" ::: "memory")
; #define PG8_WAIT_L(n) asm volatile("s_waitcnt lgkmcnt(" #n ")" ::: "memory")
; #define PG8_BAR __builtin_amdgcn_s_barrier()
; #define PG8_SCHED __builtin_amdgcn_sched_barrier(0)
; template <class Epi, class Sched, bool ALIGN_EPI = false, bool SP2 = false>
; __device__ __forceinline__ void gemm_phase(PG8_LAS unsigned char* lds, const Gemm g, const Sched& S, const Epi& E, int tid_in) {
;     ...
;             PG8_LDB(B0, 0, 0); PG8_LDB(B1, 0, 1); PG8_SCHED; PG8_LDA(At, 0, 0); PG8_STAGE(PG8_SA(1, 1), a1 + hstep, voffA);
;             PG8_WAIT_V(8); PG8_WAIT_L(0); PG8_BAR; PG8_MMA(0, 0, At, B0); PG8_MMA(0, 1, At, B1); PG8_BAR; PG8_SCHED;
;             PG8_LDA(At, 0, 1); PG8_STAGE(PG8_SB(0, 0), b2, voffB); PG8_STAGE(PG8_SB(0, 1), b2 + hstep, voffB); PG8_STAGE(PG8_SA(0, 0), a2, voffA);
;             PG8_WAIT_V(8); PG8_WAIT_L(0); PG8_BAR; PG8_MMA(1, 0, At, B0); PG8_MMA(1, 1, At, B1); PG8_BAR; PG8_SCHED;
.LBB0_388:
	s_add_u32 s20, s6, 0xfffc0080
	s_addc_u32 s21, s7, -1
	s_add_i32 s45, 0, 0x10000
	s_cmp_eq_u32 s44, 12
	s_cselect_b32 s23, s15, s21
	s_cselect_b32 s22, s40, s20
	s_cselect_b32 s21, s13, s43
	s_cselect_b32 s20, s41, s42
	s_add_i32 s48, 0, 0x14000
	v_add_u32_e32 v156, s45, v149
	v_add_u32_e32 v172, s48, v149
	ds_read_b128 v[140:143], v156
	ds_read_b128 v[144:147], v156 offset:1024
	ds_read_b128 v[152:155], v156 offset:2048
	ds_read_b128 v[156:159], v156 offset:3072
	ds_read_b128 v[160:163], v172
	ds_read_b128 v[164:167], v172 offset:1024
	ds_read_b128 v[168:171], v172 offset:2048
	ds_read_b128 v[172:175], v172 offset:3072
	s_add_i32 m0, s29, 0xc000
	ds_read_b128 v[176:179], v151
	ds_read_b128 v[180:183], v151 offset:1024
	ds_read_b128 v[184:187], v151 offset:2048
	ds_read_b128 v[188:191], v151 offset:3072
	ds_read_b128 v[204:207], v151 offset:4096
	ds_read_b128 v[208:211], v151 offset:5120
	ds_read_b128 v[212:215], v151 offset:6144
	ds_read_b128 v[216:219], v151 offset:7168
	global_load_lds_dwordx4 v136, s[6:7]
	s_add_i32 m0, s29, 0xe000
	s_nop 0
	global_load_lds_dwordx4 v138, s[6:7]
	s_waitcnt vmcnt(8)
	s_waitcnt lgkmcnt(0)
	s_barrier
	s_setprio 1
	s_waitcnt lgkmcnt(0)
	v_mfma_f32_16x16x32_bf16 v[126:129], v[140:143], v[176:179], v[126:129]
	v_mfma_f32_16x16x32_bf16 v[122:125], v[152:155], v[176:179], v[122:125]
	v_mfma_f32_16x16x32_bf16 v[110:113], v[140:143], v[184:187], v[110:113]
	v_mfma_f32_16x16x32_bf16 v[106:109], v[152:155], v[184:187], v[106:109]
	v_mfma_f32_16x16x32_bf16 v[94:97], v[140:143], v[204:207], v[94:97]
	v_mfma_f32_16x16x32_bf16 v[90:93], v[152:155], v[204:207], v[90:93]
	v_mfma_f32_16x16x32_bf16 v[78:81], v[140:143], v[212:215], v[78:81]
	v_mfma_f32_16x16x32_bf16 v[74:77], v[152:155], v[212:215], v[74:77]
	v_mfma_f32_16x16x32_bf16 v[126:129], v[144:147], v[180:183], v[126:129]
	v_mfma_f32_16x16x32_bf16 v[122:125], v[156:159], v[180:183], v[122:125]
	v_mfma_f32_16x16x32_bf16 v[110:113], v[144:147], v[188:191], v[110:113]
	v_mfma_f32_16x16x32_bf16 v[106:109], v[156:159], v[188:191], v[106:109]
	v_mfma_f32_16x16x32_bf16 v[94:97], v[144:147], v[208:211], v[94:97]
	v_mfma_f32_16x16x32_bf16 v[90:93], v[156:159], v[208:211], v[90:93]
	v_mfma_f32_16x16x32_bf16 v[78:81], v[144:147], v[216:219], v[78:81]
	v_mfma_f32_16x16x32_bf16 v[74:77], v[156:159], v[216:219], v[74:77]
	s_setprio 0
	s_setprio 1
	v_mfma_f32_16x16x32_bf16 v[118:121], v[160:163], v[176:179], v[118:121]
	v_mfma_f32_16x16x32_bf16 v[114:117], v[168:171], v[176:179], v[114:117]
	v_mfma_f32_16x16x32_bf16 v[102:105], v[160:163], v[184:187], v[102:105]
	v_mfma_f32_16x16x32_bf16 v[98:101], v[168:171], v[184:187], v[98:101]
	v_mfma_f32_16x16x32_bf16 v[86:89], v[160:163], v[204:207], v[86:89]
	v_mfma_f32_16x16x32_bf16 v[82:85], v[168:171], v[204:207], v[82:85]
	v_mfma_f32_16x16x32_bf16 v[70:73], v[160:163], v[212:215], v[70:73]
	v_mfma_f32_16x16x32_bf16 v[66:69], v[168:171], v[212:215], v[66:69]
	v_mfma_f32_16x16x32_bf16 v[118:121], v[164:167], v[180:183], v[118:121]
	v_mfma_f32_16x16x32_bf16 v[114:117], v[172:175], v[180:183], v[114:117]
	v_mfma_f32_16x16x32_bf16 v[102:105], v[164:167], v[188:191], v[102:105]
	v_mfma_f32_16x16x32_bf16 v[98:101], v[172:175], v[188:191], v[98:101]
	v_mfma_f32_16x16x32_bf16 v[86:89], v[164:167], v[208:211], v[86:89]
	v_mfma_f32_16x16x32_bf16 v[82:85], v[172:175], v[208:211], v[82:85]
	v_mfma_f32_16x16x32_bf16 v[70:73], v[164:167], v[216:219], v[70:73]
	v_mfma_f32_16x16x32_bf16 v[66:69], v[172:175], v[216:219], v[66:69]
	s_setprio 0
	s_barrier
	s_add_i32 s45, s45, s28
	v_lshl_add_u64 v[192:193], s[20:21], 0, v[32:33]
	s_mov_b32 m0, s45
	ds_read_b128 v[176:179], v151 offset:16384
	ds_read_b128 v[180:183], v151 offset:17408
	ds_read_b128 v[184:187], v151 offset:18432
	ds_read_b128 v[188:191], v151 offset:19456
	ds_read_b128 v[204:207], v151 offset:20480
	ds_read_b128 v[208:211], v151 offset:21504
	ds_read_b128 v[212:215], v151 offset:22528
	ds_read_b128 v[216:219], v151 offset:23552
	global_load_lds_dwordx4 v[192:193], off
	s_add_i32 m0, s45, 0x2000
	s_add_u32 s46, s20, 0x40000
	v_lshl_add_u64 v[220:221], s[20:21], 0, v[130:131]
	s_addc_u32 s47, s21, 0
	s_add_i32 s45, s48, s28
	global_load_lds_dwordx4 v[220:221], off
	s_mov_b32 m0, s45
	v_lshl_add_u64 v[224:225], s[22:23], 0, v[132:133]
	global_load_lds_dwordx4 v32, s[46:47]
	s_add_i32 m0, s45, 0x2000
	s_nop 0
	global_load_lds_dwordx4 v130, s[46:47]
	v_lshl_add_u64 v[222:223], s[22:23], 0, v[134:135]
	s_mov_b32 m0, s29
	s_nop 0
	global_load_lds_dwordx4 v[222:223], off
	s_mov_b32 m0, s30
	s_nop 0
	global_load_lds_dwordx4 v[224:225], off
	s_waitcnt vmcnt(8)
	s_waitcnt lgkmcnt(0)
	s_barrier
; #define PG8_STAGE(bufoff, gbase, voff) do { _Pragma("unroll") for (int _i = 0; _i < 2; ++_i) \
;         __builtin_amdgcn_global_load_lds((const unsigned*)((const char*)(gbase) + (voff)[_i]), (PG8_LAS unsigned*)(lds + (bufoff) + ldsw + _i * 8192), 16, 0, 0); } while (0)
; #define PG8_LDA(dst, b, h) do { _Pragma("unroll") for (int m = 0; m < 4; ++m) _Pragma("unroll") for (int k = 0; k < 2; ++k) dst[m][k] = *(const PG8_LAS bf16x8*)(lds + PG8_SA(b, h) + aoff + m * 2048 + k * 1024); } while (0)
; #define PG8_LDB(dst, b, h) do { _Pragma("unroll") for (int n = 0; n < 2; ++n) _Pragma("unroll") for (int k = 0; k < 2; ++k) dst[n][k] = *(const PG8_LAS bf16x8*)(lds + PG8_SB(b, h) + boff + n * 2048 + k * 1024); } while (0)
; #define PG8_MMA(ai, bj, At, Bt) do { __builtin_amdgcn_s_setprio(1); _Pragma("unroll") for (int m = 0; m < 4; ++m) _Pragma("unroll") for (int n = 0; n < 2; ++n) _Pragma("unroll") for (int k = 0; k < 2; ++k) \
;         acc[ai][bj][m][n] = __builtin_amdgcn_mfma_f32_16x16x32_bf16(Bt[n][k], At[m][k], acc[ai][bj][m][n], 0, 0, 0); __builtin_amdgcn_s_setprio(0); } while (0)
; #define PG8_WAIT_V(n) asm volatile("s_waitcnt vmcnt(" #n ")" ::: "memory")
; #define PG8_WAIT_L(n) asm volatile("s_waitcnt lgkmcnt(" #n ")" ::: "memory")
; #define PG8_BAR __builtin_amdgcn_s_barrier()
; #define PG8_SCHED __builtin_amdgcn_sched_barrier(0)
; template <class Epi, class Sched, bool ALIGN_EPI = false, bool SP2 = false>
; __device__ __forceinline__ void gemm_phase(PG8_LAS unsigned char* lds, const Gemm g, const Sched& S, const Epi& E, int tid_in) {
;     ...
;             PG8_WAIT_V(8); PG8_WAIT_L(0); PG8_BAR; PG8_MMA(1, 0, At, B0); PG8_MMA(1, 1, At, B1); PG8_BAR; PG8_SCHED;
;             PG8_LDB(B0, 1, 0); PG8_LDB(B1, 1, 1); PG8_SCHED; PG8_LDA(At, 1, 0); PG8_STAGE(PG8_SA(0, 1), a2 + hstep, voffA);
;             PG8_WAIT_V(8); PG8_WAIT_L(0); PG8_BAR; PG8_MMA(0, 0, At, B0); PG8_MMA(0, 1, At, B1); PG8_BAR; PG8_SCHED;
	s_setprio 1
	s_waitcnt lgkmcnt(0)
	v_mfma_f32_16x16x32_bf16 v[62:65], v[140:143], v[176:179], v[62:65]
	v_mfma_f32_16x16x32_bf16 v[58:61], v[152:155], v[176:179], v[58:61]
	v_mfma_f32_16x16x32_bf16 v[46:49], v[140:143], v[184:187], v[46:49]
	v_mfma_f32_16x16x32_bf16 v[42:45], v[152:155], v[184:187], v[42:45]
	v_mfma_f32_16x16x32_bf16 v[28:31], v[140:143], v[204:207], v[28:31]
	v_mfma_f32_16x16x32_bf16 v[24:27], v[152:155], v[204:207], v[24:27]
	v_mfma_f32_16x16x32_bf16 v[12:15], v[140:143], v[212:215], v[12:15]
	v_mfma_f32_16x16x32_bf16 v[8:11], v[152:155], v[212:215], v[8:11]
	v_mfma_f32_16x16x32_bf16 v[62:65], v[144:147], v[180:183], v[62:65]
	v_mfma_f32_16x16x32_bf16 v[58:61], v[156:159], v[180:183], v[58:61]
	v_mfma_f32_16x16x32_bf16 v[46:49], v[144:147], v[188:191], v[46:49]
	v_mfma_f32_16x16x32_bf16 v[42:45], v[156:159], v[188:191], v[42:45]
	v_mfma_f32_16x16x32_bf16 v[28:31], v[144:147], v[208:211], v[28:31]
	v_mfma_f32_16x16x32_bf16 v[24:27], v[156:159], v[208:211], v[24:27]
	v_mfma_f32_16x16x32_bf16 v[12:15], v[144:147], v[216:219], v[12:15]
	v_mfma_f32_16x16x32_bf16 v[8:11], v[156:159], v[216:219], v[8:11]
	s_setprio 0
	s_setprio 1
	v_mfma_f32_16x16x32_bf16 v[54:57], v[160:163], v[176:179], v[54:57]
	v_mfma_f32_16x16x32_bf16 v[50:53], v[168:171], v[176:179], v[50:53]
	v_mfma_f32_16x16x32_bf16 v[38:41], v[160:163], v[184:187], v[38:41]
	v_mfma_f32_16x16x32_bf16 v[34:37], v[168:171], v[184:187], v[34:37]
	v_mfma_f32_16x16x32_bf16 v[20:23], v[160:163], v[204:207], v[20:23]
	v_mfma_f32_16x16x32_bf16 v[16:19], v[168:171], v[204:207], v[16:19]
	v_mfma_f32_16x16x32_bf16 v[4:7], v[160:163], v[212:215], v[4:7]
	v_mfma_f32_16x16x32_bf16 v[0:3], v[168:171], v[212:215], v[0:3]
	v_mfma_f32_16x16x32_bf16 v[54:57], v[164:167], v[180:183], v[54:57]
	v_mfma_f32_16x16x32_bf16 v[50:53], v[172:175], v[180:183], v[50:53]
	v_mfma_f32_16x16x32_bf16 v[38:41], v[164:167], v[188:191], v[38:41]
	v_mfma_f32_16x16x32_bf16 v[34:37], v[172:175], v[188:191], v[34:37]
	v_mfma_f32_16x16x32_bf16 v[20:23], v[164:167], v[208:211], v[20:23]
	v_mfma_f32_16x16x32_bf16 v[16:19], v[172:175], v[208:211], v[16:19]
	v_mfma_f32_16x16x32_bf16 v[4:7], v[164:167], v[216:219], v[4:7]
	v_mfma_f32_16x16x32_bf16 v[0:3], v[172:175], v[216:219], v[0:3]
	s_setprio 0
	s_barrier
	s_add_i32 s45, 0, 0x18000
	s_add_i32 s46, 0, 0x1c000
	v_add_u32_e32 v156, s45, v149
	v_add_u32_e32 v172, s46, v149
	ds_read_b128 v[140:143], v156
	ds_read_b128 v[144:147], v156 offset:1024
	ds_read_b128 v[152:155], v156 offset:2048
	ds_read_b128 v[156:159], v156 offset:3072
	ds_read_b128 v[160:163], v172
	ds_read_b128 v[164:167], v172 offset:1024
	ds_read_b128 v[168:171], v172 offset:2048
	ds_read_b128 v[172:175], v172 offset:3072
	s_add_u32 s22, s22, 0x40000
	s_addc_u32 s23, s23, 0
	s_mov_b32 m0, s31
	ds_read_b128 v[176:179], v151 offset:32768
	ds_read_b128 v[180:183], v151 offset:33792
	ds_read_b128 v[184:187], v151 offset:34816
	ds_read_b128 v[188:191], v151 offset:35840
	ds_read_b128 v[204:207], v151 offset:36864
	ds_read_b128 v[208:211], v151 offset:37888
	ds_read_b128 v[212:215], v151 offset:38912
	ds_read_b128 v[216:219], v151 offset:39936
	global_load_lds_dwordx4 v134, s[22:23]
	s_mov_b32 m0, s34
	s_nop 0
	global_load_lds_dwordx4 v132, s[22:23]
	s_waitcnt vmcnt(8)
	s_waitcnt lgkmcnt(0)
	s_barrier
	s_setprio 1
	s_waitcnt lgkmcnt(0)
	v_mfma_f32_16x16x32_bf16 v[126:129], v[140:143], v[176:179], v[126:129]
	v_mfma_f32_16x16x32_bf16 v[122:125], v[152:155], v[176:179], v[122:125]
	v_mfma_f32_16x16x32_bf16 v[110:113], v[140:143], v[184:187], v[110:113]
	v_mfma_f32_16x16x32_bf16 v[106:109], v[152:155], v[184:187], v[106:109]
	v_mfma_f32_16x16x32_bf16 v[94:97], v[140:143], v[204:207], v[94:97]
	v_mfma_f32_16x16x32_bf16 v[90:93], v[152:155], v[204:207], v[90:93]
	v_mfma_f32_16x16x32_bf16 v[78:81], v[140:143], v[212:215], v[78:81]
	v_mfma_f32_16x16x32_bf16 v[74:77], v[152:155], v[212:215], v[74:77]
	v_mfma_f32_16x16x32_bf16 v[126:129], v[144:147], v[180:183], v[126:129]
	v_mfma_f32_16x16x32_bf16 v[122:125], v[156:159], v[180:183], v[122:125]
	v_mfma_f32_16x16x32_bf16 v[110:113], v[144:147], v[188:191], v[110:113]
	v_mfma_f32_16x16x32_bf16 v[106:109], v[156:159], v[188:191], v[106:109]
	v_mfma_f32_16x16x32_bf16 v[94:97], v[144:147], v[208:211], v[94:97]
	v_mfma_f32_16x16x32_bf16 v[90:93], v[156:159], v[208:211], v[90:93]
	v_mfma_f32_16x16x32_bf16 v[78:81], v[144:147], v[216:219], v[78:81]
	v_mfma_f32_16x16x32_bf16 v[74:77], v[156:159], v[216:219], v[74:77]
	s_setprio 0
	s_setprio 1
	v_mfma_f32_16x16x32_bf16 v[118:121], v[160:163], v[176:179], v[118:121]
	v_mfma_f32_16x16x32_bf16 v[114:117], v[168:171], v[176:179], v[114:117]
	v_mfma_f32_16x16x32_bf16 v[102:105], v[160:163], v[184:187], v[102:105]
	v_mfma_f32_16x16x32_bf16 v[98:101], v[168:171], v[184:187], v[98:101]
	v_mfma_f32_16x16x32_bf16 v[86:89], v[160:163], v[204:207], v[86:89]
	v_mfma_f32_16x16x32_bf16 v[82:85], v[168:171], v[204:207], v[82:85]
	v_mfma_f32_16x16x32_bf16 v[70:73], v[160:163], v[212:215], v[70:73]
	v_mfma_f32_16x16x32_bf16 v[66:69], v[168:171], v[212:215], v[66:69]
	v_mfma_f32_16x16x32_bf16 v[118:121], v[164:167], v[180:183], v[118:121]
	v_mfma_f32_16x16x32_bf16 v[114:117], v[172:175], v[180:183], v[114:117]
	v_mfma_f32_16x16x32_bf16 v[102:105], v[164:167], v[188:191], v[102:105]
	v_mfma_f32_16x16x32_bf16 v[98:101], v[172:175], v[188:191], v[98:101]
	v_mfma_f32_16x16x32_bf16 v[86:89], v[164:167], v[208:211], v[86:89]
	v_mfma_f32_16x16x32_bf16 v[82:85], v[172:175], v[208:211], v[82:85]
	v_mfma_f32_16x16x32_bf16 v[70:73], v[164:167], v[216:219], v[70:73]
	v_mfma_f32_16x16x32_bf16 v[66:69], v[172:175], v[216:219], v[66:69]
	s_setprio 0
	s_barrier
; #define PG8_STAGE(bufoff, gbase, voff) do { _Pragma("unroll") for (int _i = 0; _i < 2; ++_i) \
;         __builtin_amdgcn_global_load_lds((const unsigned*)((const char*)(gbase) + (voff)[_i]), (PG8_LAS unsigned*)(lds + (bufoff) + ldsw + _i * 8192), 16, 0, 0); } while (0)
; #define PG8_LDA(dst, b, h) do { _Pragma("unroll") for (int m = 0; m < 4; ++m) _Pragma("unroll") for (int k = 0; k < 2; ++k) dst[m][k] = *(const PG8_LAS bf16x8*)(lds + PG8_SA(b, h) + aoff + m * 2048 + k * 1024); } while (0)
; #define PG8_WAIT_V(n) asm volatile("s_waitcnt vmcnt(" #n ")" ::: "memory")
; #define PG8_WAIT_L(n) asm volatile("s_waitcnt lgkmcnt(" #n ")" ::: "memory")
; #define PG8_BAR __builtin_amdgcn_s_barrier()
; template <class Epi, class Sched, bool ALIGN_EPI = false, bool SP2 = false>
; __device__ __forceinline__ void gemm_phase(PG8_LAS unsigned char* lds, const Gemm g, const Sched& S, const Epi& E, int tid_in) {
;     ...
;         for (int t = 0; t < nt; t += 2) {
;             const bool last = (t == nt - 2);
;             const char* a1 = cA + (size_t)(t + 1) * kstep;
;             const char* a2 = last ? nA : cA + (size_t)(t + 2) * kstep; const char* b2 = last ? nB : cB + (size_t)(t + 2) * kstep;
;             const char* a3 = a2 + kstep; const char* b3 = b2 + kstep;
;             if (last && has_next) S.a_ready(nxt);
;             if constexpr (SP2) {
;             PG8_LDB(B0, 0, 0); PG8_LDB(B1, 0, 1); PG8_SCHED; PG8_LDA(At, 0, 0); PG8_STAGE(PG8_SA(1, 1), a1 + hstep, voffA);
;             PG8_WAIT_V(8); PG8_WAIT_L(0); PG8_BAR; PG8_MMA(0, 0, At, B0); PG8_MMA(0, 1, At, B1); PG8_BAR; PG8_SCHED;
;             PG8_LDA(At, 0, 1); PG8_STAGE(PG8_SB(0, 0), b2, voffB); PG8_STAGE(PG8_SB(0, 1), b2 + hstep, voffB); PG8_STAGE(PG8_SA(0, 0), a2, voffA);
;             PG8_WAIT_V(8); PG8_WAIT_L(0); PG8_BAR; PG8_MMA(1, 0, At, B0); PG8_MMA(1, 1, At, B1); PG8_BAR; PG8_SCHED;
;             PG8_LDB(B0, 1, 0); PG8_LDB(B1, 1, 1); PG8_SCHED; PG8_LDA(At, 1, 0); PG8_STAGE(PG8_SA(0, 1), a2 + hstep, voffA);
;             PG8_WAIT_V(8); PG8_WAIT_L(0); PG8_BAR; PG8_MMA(0, 0, At, B0); PG8_MMA(0, 1, At, B1); PG8_BAR; PG8_SCHED;
;             PG8_LDA(At, 1, 1); PG8_STAGE(PG8_SB(1, 0), b3, voffB); PG8_STAGE(PG8_SB(1, 1), b3 + hstep, voffB); PG8_STAGE(PG8_SA(1, 0), a3, voffA);
;             PG8_WAIT_V(8); PG8_WAIT_L(0); PG8_BAR; PG8_MMA(1, 0, At, B0); PG8_MMA(1, 1, At, B1); PG8_BAR; PG8_SCHED;
	s_add_i32 s22, s45, s28
	v_lshl_add_u64 v[192:193], v[192:193], 0, s[84:85]
	s_mov_b32 m0, s22
	ds_read_b128 v[176:179], v151 offset:49152
	ds_read_b128 v[180:183], v151 offset:50176
	ds_read_b128 v[184:187], v151 offset:51200
	ds_read_b128 v[188:191], v151 offset:52224
	ds_read_b128 v[204:207], v151 offset:53248
	ds_read_b128 v[208:211], v151 offset:54272
	ds_read_b128 v[212:215], v151 offset:55296
	ds_read_b128 v[216:219], v151 offset:56320
	global_load_lds_dwordx4 v[192:193], off
	s_add_i32 m0, s22, 0x2000
	s_add_u32 s20, s20, 0x40080
	v_lshl_add_u64 v[192:193], v[220:221], 0, s[84:85]
	s_addc_u32 s21, s21, 0
	s_add_i32 s22, s46, s28
	global_load_lds_dwordx4 v[192:193], off
	s_mov_b32 m0, s22
	s_nop 0
	global_load_lds_dwordx4 v32, s[20:21]
	s_add_i32 m0, s22, 0x2000
	s_nop 0
	global_load_lds_dwordx4 v130, s[20:21]
	v_lshl_add_u64 v[192:193], v[222:223], 0, s[84:85]
	s_mov_b32 m0, s35
	s_nop 0
	global_load_lds_dwordx4 v[192:193], off
	v_lshl_add_u64 v[192:193], v[224:225], 0, s[84:85]
	s_mov_b32 m0, s36
	s_nop 0
	global_load_lds_dwordx4 v[192:193], off
	s_waitcnt vmcnt(8)
	s_waitcnt lgkmcnt(0)
	s_barrier
	s_setprio 1
	s_waitcnt lgkmcnt(0)
	v_mfma_f32_16x16x32_bf16 v[62:65], v[140:143], v[176:179], v[62:65]
	v_mfma_f32_16x16x32_bf16 v[58:61], v[152:155], v[176:179], v[58:61]
	v_mfma_f32_16x16x32_bf16 v[46:49], v[140:143], v[184:187], v[46:49]
	v_mfma_f32_16x16x32_bf16 v[42:45], v[152:155], v[184:187], v[42:45]
	v_mfma_f32_16x16x32_bf16 v[28:31], v[140:143], v[204:207], v[28:31]
	v_mfma_f32_16x16x32_bf16 v[24:27], v[152:155], v[204:207], v[24:27]
	v_mfma_f32_16x16x32_bf16 v[12:15], v[140:143], v[212:215], v[12:15]
	v_mfma_f32_16x16x32_bf16 v[8:11], v[152:155], v[212:215], v[8:11]
	v_mfma_f32_16x16x32_bf16 v[62:65], v[144:147], v[180:183], v[62:65]
	v_mfma_f32_16x16x32_bf16 v[58:61], v[156:159], v[180:183], v[58:61]
	v_mfma_f32_16x16x32_bf16 v[46:49], v[144:147], v[188:191], v[46:49]
	v_mfma_f32_16x16x32_bf16 v[42:45], v[156:159], v[188:191], v[42:45]
	v_mfma_f32_16x16x32_bf16 v[28:31], v[144:147], v[208:211], v[28:31]
	v_mfma_f32_16x16x32_bf16 v[24:27], v[156:159], v[208:211], v[24:27]
	v_mfma_f32_16x16x32_bf16 v[12:15], v[144:147], v[216:219], v[12:15]
	v_mfma_f32_16x16x32_bf16 v[8:11], v[156:159], v[216:219], v[8:11]
	s_setprio 0
	s_setprio 1
	v_mfma_f32_16x16x32_bf16 v[54:57], v[160:163], v[176:179], v[54:57]
	v_mfma_f32_16x16x32_bf16 v[50:53], v[168:171], v[176:179], v[50:53]
	v_mfma_f32_16x16x32_bf16 v[38:41], v[160:163], v[184:187], v[38:41]
	v_mfma_f32_16x16x32_bf16 v[34:37], v[168:171], v[184:187], v[34:37]
	v_mfma_f32_16x16x32_bf16 v[20:23], v[160:163], v[204:207], v[20:23]
	v_mfma_f32_16x16x32_bf16 v[16:19], v[168:171], v[204:207], v[16:19]
	v_mfma_f32_16x16x32_bf16 v[4:7], v[160:163], v[212:215], v[4:7]
	v_mfma_f32_16x16x32_bf16 v[0:3], v[168:171], v[212:215], v[0:3]
	v_mfma_f32_16x16x32_bf16 v[54:57], v[164:167], v[180:183], v[54:57]
	v_mfma_f32_16x16x32_bf16 v[50:53], v[172:175], v[180:183], v[50:53]
	v_mfma_f32_16x16x32_bf16 v[38:41], v[164:167], v[188:191], v[38:41]
	v_mfma_f32_16x16x32_bf16 v[34:37], v[172:175], v[188:191], v[34:37]
	v_mfma_f32_16x16x32_bf16 v[20:23], v[164:167], v[208:211], v[20:23]
	v_mfma_f32_16x16x32_bf16 v[16:19], v[172:175], v[208:211], v[16:19]
	v_mfma_f32_16x16x32_bf16 v[4:7], v[164:167], v[216:219], v[4:7]
	v_mfma_f32_16x16x32_bf16 v[0:3], v[172:175], v[216:219], v[0:3]
	s_setprio 0
	s_barrier
	s_add_i32 s44, s44, 2
	s_add_u32 s6, s6, 0x100
	s_addc_u32 s7, s7, 0
	s_add_u32 s42, s42, 0x100
	s_addc_u32 s43, s43, 0
	s_cmp_gt_u32 s44, 13
	s_cbranch_scc0 .LBB0_388
	s_and_b64 vcc, exec, s[10:11]
	s_cbranch_vccz .LBB0_391
	s_barrier

; #define PG8_STAGE(bufoff, gbase, voff) do { _Pragma("unroll") for (int _i = 0; _i < 2; ++_i) \
;         __builtin_amdgcn_global_load_lds((const unsigned*)((const char*)(gbase) + (voff)[_i]), (PG8_LAS unsigned*)(lds + (bufoff) + ldsw + _i * 8192), 16, 0, 0); } while (0)
; #define PG8_LDA(dst, b, h) do { _Pragma("unroll") for (int m = 0; m < 4; ++m) _Pragma("unroll") for (int k = 0; k < 2; ++k) dst[m][k] = *(const PG8_LAS bf16x8*)(lds + PG8_SA(b, h) + aoff + m * 2048 + k * 1024); } while (0)
; #define PG8_LDB(dst, b, h) do { _Pragma("unroll") for (int n = 0; n < 2; ++n) _Pragma("unroll") for (int k = 0; k < 2; ++k) dst[n][k] = *(const PG8_LAS bf16x8*)(lds + PG8_SB(b, h) + boff + n * 2048 + k * 1024); } while (0)
; #define PG8_MMA(ai, bj, At, Bt) do { __builtin_amdgcn_s_setprio(1); _Pragma("unroll") for (int m = 0; m < 4; ++m) _Pragma("unroll") for (int n = 0; n < 2; ++n) _Pragma("unroll") for (int k = 0; k < 2; ++k) \
;         acc[ai][bj][m][n] = __builtin_amdgcn_mfma_f32_16x16x32_bf16(Bt[n][k], At[m][k], acc[ai][bj][m][n], 0, 0, 0); __builtin_amdgcn_s_setprio(0); } while (0)
; #define PG8_WAIT_V(n) asm volatile("s_waitcnt vmcnt(" #n ")" ::: "memory")
; #define PG8_WAIT_L(n) asm volatile("s_waitcnt lgkmcnt(" #n ")" ::: "memory")
; #define PG8_BAR __builtin_amdgcn_s_barrier()
; #define PG8_SCHED __builtin_amdgcn_sched_barrier(0)
; template <class Epi, class Sched, bool ALIGN_EPI = false, bool SP2 = false>
; __device__ __forceinline__ void gemm_phase(PG8_LAS unsigned char* lds, const Gemm g, const Sched& S, const Epi& E, int tid_in) {
;     ...
;             PG8_LDB(B0, 0, 0); PG8_LDB(B1, 0, 1); PG8_SCHED; PG8_LDA(At, 0, 0); PG8_STAGE(PG8_SA(1, 1), a1 + hstep, voffA);
;             PG8_WAIT_V(8); PG8_WAIT_L(0); PG8_BAR; PG8_MMA(0, 0, At, B0); PG8_MMA(0, 1, At, B1); PG8_BAR; PG8_SCHED;
;             PG8_LDA(At, 0, 1); PG8_STAGE(PG8_SB(0, 0), b2, voffB); PG8_STAGE(PG8_SB(0, 1), b2 + hstep, voffB); PG8_STAGE(PG8_SA(0, 0), a2, voffA);
;             PG8_WAIT_V(8); PG8_WAIT_L(0); PG8_BAR; PG8_MMA(1, 0, At, B0); PG8_MMA(1, 1, At, B1); PG8_BAR; PG8_SCHED;
.LBB0_920:
	s_add_u32 s26, s2, 0xfffc0080
	s_addc_u32 s27, s3, -1
	s_add_i32 s51, 0, 0x10000
	s_cmp_eq_u32 s50, 12
	s_cselect_b32 s29, s21, s27
	s_cselect_b32 s28, s46, s26
	s_cselect_b32 s27, s19, s49
	s_cselect_b32 s26, s47, s48
	s_add_i32 s54, 0, 0x14000
	v_add_u32_e32 v142, s51, v217
	v_add_u32_e32 v158, s54, v217
	ds_read_b128 v[130:133], v142
	ds_read_b128 v[134:137], v142 offset:1024
	ds_read_b128 v[138:141], v142 offset:2048
	ds_read_b128 v[142:145], v142 offset:3072
	ds_read_b128 v[146:149], v158
	ds_read_b128 v[150:153], v158 offset:1024
	ds_read_b128 v[154:157], v158 offset:2048
	ds_read_b128 v[158:161], v158 offset:3072
	s_add_i32 m0, s37, 0xc000
	ds_read_b128 v[162:165], v219
	ds_read_b128 v[166:169], v219 offset:1024
	ds_read_b128 v[170:173], v219 offset:2048
	ds_read_b128 v[174:177], v219 offset:3072
	ds_read_b128 v[188:191], v219 offset:4096
	ds_read_b128 v[204:207], v219 offset:5120
	ds_read_b128 v[208:211], v219 offset:6144
	ds_read_b128 v[212:215], v219 offset:7168
	global_load_lds_dwordx4 v184, s[2:3]
	s_add_i32 m0, s37, 0xe000
	s_nop 0
	global_load_lds_dwordx4 v186, s[2:3]
	s_waitcnt vmcnt(8)
	s_waitcnt lgkmcnt(0)
	s_barrier
	s_setprio 1
	s_waitcnt lgkmcnt(0)
	v_mfma_f32_16x16x32_bf16 v[126:129], v[130:133], v[162:165], v[126:129]
	v_mfma_f32_16x16x32_bf16 v[122:125], v[138:141], v[162:165], v[122:125]
	v_mfma_f32_16x16x32_bf16 v[110:113], v[130:133], v[170:173], v[110:113]
	v_mfma_f32_16x16x32_bf16 v[106:109], v[138:141], v[170:173], v[106:109]
	v_mfma_f32_16x16x32_bf16 v[94:97], v[130:133], v[188:191], v[94:97]
	v_mfma_f32_16x16x32_bf16 v[90:93], v[138:141], v[188:191], v[90:93]
	v_mfma_f32_16x16x32_bf16 v[78:81], v[130:133], v[208:211], v[78:81]
	v_mfma_f32_16x16x32_bf16 v[74:77], v[138:141], v[208:211], v[74:77]
	v_mfma_f32_16x16x32_bf16 v[126:129], v[134:137], v[166:169], v[126:129]
	v_mfma_f32_16x16x32_bf16 v[122:125], v[142:145], v[166:169], v[122:125]
	v_mfma_f32_16x16x32_bf16 v[110:113], v[134:137], v[174:177], v[110:113]
	v_mfma_f32_16x16x32_bf16 v[106:109], v[142:145], v[174:177], v[106:109]
	v_mfma_f32_16x16x32_bf16 v[94:97], v[134:137], v[204:207], v[94:97]
	v_mfma_f32_16x16x32_bf16 v[90:93], v[142:145], v[204:207], v[90:93]
	v_mfma_f32_16x16x32_bf16 v[78:81], v[134:137], v[212:215], v[78:81]
	v_mfma_f32_16x16x32_bf16 v[74:77], v[142:145], v[212:215], v[74:77]
	s_setprio 0
	s_setprio 1
	v_mfma_f32_16x16x32_bf16 v[118:121], v[146:149], v[162:165], v[118:121]
	v_mfma_f32_16x16x32_bf16 v[114:117], v[154:157], v[162:165], v[114:117]
	v_mfma_f32_16x16x32_bf16 v[102:105], v[146:149], v[170:173], v[102:105]
	v_mfma_f32_16x16x32_bf16 v[98:101], v[154:157], v[170:173], v[98:101]
	v_mfma_f32_16x16x32_bf16 v[86:89], v[146:149], v[188:191], v[86:89]
	v_mfma_f32_16x16x32_bf16 v[82:85], v[154:157], v[188:191], v[82:85]
	v_mfma_f32_16x16x32_bf16 v[70:73], v[146:149], v[208:211], v[70:73]
	v_mfma_f32_16x16x32_bf16 v[66:69], v[154:157], v[208:211], v[66:69]
	v_mfma_f32_16x16x32_bf16 v[118:121], v[150:153], v[166:169], v[118:121]
	v_mfma_f32_16x16x32_bf16 v[114:117], v[158:161], v[166:169], v[114:117]
	v_mfma_f32_16x16x32_bf16 v[102:105], v[150:153], v[174:177], v[102:105]
	v_mfma_f32_16x16x32_bf16 v[98:101], v[158:161], v[174:177], v[98:101]
	v_mfma_f32_16x16x32_bf16 v[86:89], v[150:153], v[204:207], v[86:89]
	v_mfma_f32_16x16x32_bf16 v[82:85], v[158:161], v[204:207], v[82:85]
	v_mfma_f32_16x16x32_bf16 v[70:73], v[150:153], v[212:215], v[70:73]
	v_mfma_f32_16x16x32_bf16 v[66:69], v[158:161], v[212:215], v[66:69]
	s_setprio 0
	s_barrier
	s_add_i32 s51, s51, s36
	v_lshl_add_u64 v[192:193], s[26:27], 0, v[32:33]
	s_mov_b32 m0, s51
	ds_read_b128 v[162:165], v219 offset:16384
	ds_read_b128 v[166:169], v219 offset:17408
	ds_read_b128 v[170:173], v219 offset:18432
	ds_read_b128 v[174:177], v219 offset:19456
	ds_read_b128 v[188:191], v219 offset:20480
	ds_read_b128 v[204:207], v219 offset:21504
	ds_read_b128 v[208:211], v219 offset:22528
	ds_read_b128 v[212:215], v219 offset:23552
	global_load_lds_dwordx4 v[192:193], off
	s_add_i32 m0, s51, 0x2000
	s_add_u32 s52, s26, 0x40000
	v_lshl_add_u64 v[220:221], s[26:27], 0, v[178:179]
	s_addc_u32 s53, s27, 0
	s_add_i32 s51, s54, s36
	global_load_lds_dwordx4 v[220:221], off
	s_mov_b32 m0, s51
	v_lshl_add_u64 v[224:225], s[28:29], 0, v[180:181]
	global_load_lds_dwordx4 v32, s[52:53]
	s_add_i32 m0, s51, 0x2000
	s_nop 0
	global_load_lds_dwordx4 v178, s[52:53]
	v_lshl_add_u64 v[222:223], s[28:29], 0, v[182:183]
	s_mov_b32 m0, s37
	s_nop 0
	global_load_lds_dwordx4 v[222:223], off
	s_mov_b32 m0, s38
	s_nop 0
	global_load_lds_dwordx4 v[224:225], off
	s_waitcnt vmcnt(8)
	s_waitcnt lgkmcnt(0)
	s_barrier
; #define PG8_STAGE(bufoff, gbase, voff) do { _Pragma("unroll") for (int _i = 0; _i < 2; ++_i) \
;         __builtin_amdgcn_global_load_lds((const unsigned*)((const char*)(gbase) + (voff)[_i]), (PG8_LAS unsigned*)(lds + (bufoff) + ldsw + _i * 8192), 16, 0, 0); } while (0)
; #define PG8_LDA(dst, b, h) do { _Pragma("unroll") for (int m = 0; m < 4; ++m) _Pragma("unroll") for (int k = 0; k < 2; ++k) dst[m][k] = *(const PG8_LAS bf16x8*)(lds + PG8_SA(b, h) + aoff + m * 2048 + k * 1024); } while (0)
; #define PG8_LDB(dst, b, h) do { _Pragma("unroll") for (int n = 0; n < 2; ++n) _Pragma("unroll") for (int k = 0; k < 2; ++k) dst[n][k] = *(const PG8_LAS bf16x8*)(lds + PG8_SB(b, h) + boff + n * 2048 + k * 1024); } while (0)
; #define PG8_MMA(ai, bj, At, Bt) do { __builtin_amdgcn_s_setprio(1); _Pragma("unroll") for (int m = 0; m < 4; ++m) _Pragma("unroll") for (int n = 0; n < 2; ++n) _Pragma("unroll") for (int k = 0; k < 2; ++k) \
;         acc[ai][bj][m][n] = __builtin_amdgcn_mfma_f32_16x16x32_bf16(Bt[n][k], At[m][k], acc[ai][bj][m][n], 0, 0, 0); __builtin_amdgcn_s_setprio(0); } while (0)
; #define PG8_WAIT_V(n) asm volatile("s_waitcnt vmcnt(" #n ")" ::: "memory")
; #define PG8_WAIT_L(n) asm volatile("s_waitcnt lgkmcnt(" #n ")" ::: "memory")
; #define PG8_BAR __builtin_amdgcn_s_barrier()
; #define PG8_SCHED __builtin_amdgcn_sched_barrier(0)
; template <class Epi, class Sched, bool ALIGN_EPI = false, bool SP2 = false>
; __device__ __forceinline__ void gemm_phase(PG8_LAS unsigned char* lds, const Gemm g, const Sched& S, const Epi& E, int tid_in) {
;     ...
;             PG8_WAIT_V(8); PG8_WAIT_L(0); PG8_BAR; PG8_MMA(1, 0, At, B0); PG8_MMA(1, 1, At, B1); PG8_BAR; PG8_SCHED;
;             PG8_LDB(B0, 1, 0); PG8_LDB(B1, 1, 1); PG8_SCHED; PG8_LDA(At, 1, 0); PG8_STAGE(PG8_SA(0, 1), a2 + hstep, voffA);
;             PG8_WAIT_V(8); PG8_WAIT_L(0); PG8_BAR; PG8_MMA(0, 0, At, B0); PG8_MMA(0, 1, At, B1); PG8_BAR; PG8_SCHED;
	s_setprio 1
	s_waitcnt lgkmcnt(0)
	v_mfma_f32_16x16x32_bf16 v[62:65], v[130:133], v[162:165], v[62:65]
	v_mfma_f32_16x16x32_bf16 v[58:61], v[138:141], v[162:165], v[58:61]
	v_mfma_f32_16x16x32_bf16 v[46:49], v[130:133], v[170:173], v[46:49]
	v_mfma_f32_16x16x32_bf16 v[42:45], v[138:141], v[170:173], v[42:45]
	v_mfma_f32_16x16x32_bf16 v[28:31], v[130:133], v[188:191], v[28:31]
	v_mfma_f32_16x16x32_bf16 v[24:27], v[138:141], v[188:191], v[24:27]
	v_mfma_f32_16x16x32_bf16 v[12:15], v[130:133], v[208:211], v[12:15]
	v_mfma_f32_16x16x32_bf16 v[8:11], v[138:141], v[208:211], v[8:11]
	v_mfma_f32_16x16x32_bf16 v[62:65], v[134:137], v[166:169], v[62:65]
	v_mfma_f32_16x16x32_bf16 v[58:61], v[142:145], v[166:169], v[58:61]
	v_mfma_f32_16x16x32_bf16 v[46:49], v[134:137], v[174:177], v[46:49]
	v_mfma_f32_16x16x32_bf16 v[42:45], v[142:145], v[174:177], v[42:45]
	v_mfma_f32_16x16x32_bf16 v[28:31], v[134:137], v[204:207], v[28:31]
	v_mfma_f32_16x16x32_bf16 v[24:27], v[142:145], v[204:207], v[24:27]
	v_mfma_f32_16x16x32_bf16 v[12:15], v[134:137], v[212:215], v[12:15]
	v_mfma_f32_16x16x32_bf16 v[8:11], v[142:145], v[212:215], v[8:11]
	s_setprio 0
	s_setprio 1
	v_mfma_f32_16x16x32_bf16 v[54:57], v[146:149], v[162:165], v[54:57]
	v_mfma_f32_16x16x32_bf16 v[50:53], v[154:157], v[162:165], v[50:53]
	v_mfma_f32_16x16x32_bf16 v[38:41], v[146:149], v[170:173], v[38:41]
	v_mfma_f32_16x16x32_bf16 v[34:37], v[154:157], v[170:173], v[34:37]
	v_mfma_f32_16x16x32_bf16 v[20:23], v[146:149], v[188:191], v[20:23]
	v_mfma_f32_16x16x32_bf16 v[16:19], v[154:157], v[188:191], v[16:19]
	v_mfma_f32_16x16x32_bf16 v[4:7], v[146:149], v[208:211], v[4:7]
	v_mfma_f32_16x16x32_bf16 v[0:3], v[154:157], v[208:211], v[0:3]
	v_mfma_f32_16x16x32_bf16 v[54:57], v[150:153], v[166:169], v[54:57]
	v_mfma_f32_16x16x32_bf16 v[50:53], v[158:161], v[166:169], v[50:53]
	v_mfma_f32_16x16x32_bf16 v[38:41], v[150:153], v[174:177], v[38:41]
	v_mfma_f32_16x16x32_bf16 v[34:37], v[158:161], v[174:177], v[34:37]
	v_mfma_f32_16x16x32_bf16 v[20:23], v[150:153], v[204:207], v[20:23]
	v_mfma_f32_16x16x32_bf16 v[16:19], v[158:161], v[204:207], v[16:19]
	v_mfma_f32_16x16x32_bf16 v[4:7], v[150:153], v[212:215], v[4:7]
	v_mfma_f32_16x16x32_bf16 v[0:3], v[158:161], v[212:215], v[0:3]
	s_setprio 0
	s_barrier
	s_add_i32 s51, 0, 0x18000
	s_add_i32 s52, 0, 0x1c000
	v_add_u32_e32 v142, s51, v217
	v_add_u32_e32 v158, s52, v217
	ds_read_b128 v[130:133], v142
	ds_read_b128 v[134:137], v142 offset:1024
	ds_read_b128 v[138:141], v142 offset:2048
	ds_read_b128 v[142:145], v142 offset:3072
	ds_read_b128 v[146:149], v158
	ds_read_b128 v[150:153], v158 offset:1024
	ds_read_b128 v[154:157], v158 offset:2048
	ds_read_b128 v[158:161], v158 offset:3072
	s_add_u32 s28, s28, 0x40000
	s_addc_u32 s29, s29, 0
	s_mov_b32 m0, s39
	ds_read_b128 v[162:165], v219 offset:32768
	ds_read_b128 v[166:169], v219 offset:33792
	ds_read_b128 v[170:173], v219 offset:34816
	ds_read_b128 v[174:177], v219 offset:35840
	ds_read_b128 v[188:191], v219 offset:36864
	ds_read_b128 v[204:207], v219 offset:37888
	ds_read_b128 v[208:211], v219 offset:38912
	ds_read_b128 v[212:215], v219 offset:39936
	global_load_lds_dwordx4 v182, s[28:29]
	s_mov_b32 m0, s40
	s_nop 0
	global_load_lds_dwordx4 v180, s[28:29]
	s_waitcnt vmcnt(8)
	s_waitcnt lgkmcnt(0)
	s_barrier
	s_setprio 1
	s_waitcnt lgkmcnt(0)
	v_mfma_f32_16x16x32_bf16 v[126:129], v[130:133], v[162:165], v[126:129]
	v_mfma_f32_16x16x32_bf16 v[122:125], v[138:141], v[162:165], v[122:125]
	v_mfma_f32_16x16x32_bf16 v[110:113], v[130:133], v[170:173], v[110:113]
	v_mfma_f32_16x16x32_bf16 v[106:109], v[138:141], v[170:173], v[106:109]
	v_mfma_f32_16x16x32_bf16 v[94:97], v[130:133], v[188:191], v[94:97]
	v_mfma_f32_16x16x32_bf16 v[90:93], v[138:141], v[188:191], v[90:93]
	v_mfma_f32_16x16x32_bf16 v[78:81], v[130:133], v[208:211], v[78:81]
	v_mfma_f32_16x16x32_bf16 v[74:77], v[138:141], v[208:211], v[74:77]
	v_mfma_f32_16x16x32_bf16 v[126:129], v[134:137], v[166:169], v[126:129]
	v_mfma_f32_16x16x32_bf16 v[122:125], v[142:145], v[166:169], v[122:125]
	v_mfma_f32_16x16x32_bf16 v[110:113], v[134:137], v[174:177], v[110:113]
	v_mfma_f32_16x16x32_bf16 v[106:109], v[142:145], v[174:177], v[106:109]
	v_mfma_f32_16x16x32_bf16 v[94:97], v[134:137], v[204:207], v[94:97]
	v_mfma_f32_16x16x32_bf16 v[90:93], v[142:145], v[204:207], v[90:93]
	v_mfma_f32_16x16x32_bf16 v[78:81], v[134:137], v[212:215], v[78:81]
	v_mfma_f32_16x16x32_bf16 v[74:77], v[142:145], v[212:215], v[74:77]
	s_setprio 0
	s_setprio 1
	v_mfma_f32_16x16x32_bf16 v[118:121], v[146:149], v[162:165], v[118:121]
	v_mfma_f32_16x16x32_bf16 v[114:117], v[154:157], v[162:165], v[114:117]
	v_mfma_f32_16x16x32_bf16 v[102:105], v[146:149], v[170:173], v[102:105]
	v_mfma_f32_16x16x32_bf16 v[98:101], v[154:157], v[170:173], v[98:101]
	v_mfma_f32_16x16x32_bf16 v[86:89], v[146:149], v[188:191], v[86:89]
	v_mfma_f32_16x16x32_bf16 v[82:85], v[154:157], v[188:191], v[82:85]
	v_mfma_f32_16x16x32_bf16 v[70:73], v[146:149], v[208:211], v[70:73]
	v_mfma_f32_16x16x32_bf16 v[66:69], v[154:157], v[208:211], v[66:69]
	v_mfma_f32_16x16x32_bf16 v[118:121], v[150:153], v[166:169], v[118:121]
	v_mfma_f32_16x16x32_bf16 v[114:117], v[158:161], v[166:169], v[114:117]
	v_mfma_f32_16x16x32_bf16 v[102:105], v[150:153], v[174:177], v[102:105]
	v_mfma_f32_16x16x32_bf16 v[98:101], v[158:161], v[174:177], v[98:101]
	v_mfma_f32_16x16x32_bf16 v[86:89], v[150:153], v[204:207], v[86:89]
	v_mfma_f32_16x16x32_bf16 v[82:85], v[158:161], v[204:207], v[82:85]
	v_mfma_f32_16x16x32_bf16 v[70:73], v[150:153], v[212:215], v[70:73]
	v_mfma_f32_16x16x32_bf16 v[66:69], v[158:161], v[212:215], v[66:69]
	s_setprio 0
	s_barrier
; #define PG8_STAGE(bufoff, gbase, voff) do { _Pragma("unroll") for (int _i = 0; _i < 2; ++_i) \
;         __builtin_amdgcn_global_load_lds((const unsigned*)((const char*)(gbase) + (voff)[_i]), (PG8_LAS unsigned*)(lds + (bufoff) + ldsw + _i * 8192), 16, 0, 0); } while (0)
; #define PG8_LDA(dst, b, h) do { _Pragma("unroll") for (int m = 0; m < 4; ++m) _Pragma("unroll") for (int k = 0; k < 2; ++k) dst[m][k] = *(const PG8_LAS bf16x8*)(lds + PG8_SA(b, h) + aoff + m * 2048 + k * 1024); } while (0)
; #define PG8_WAIT_V(n) asm volatile("s_waitcnt vmcnt(" #n ")" ::: "memory")
; #define PG8_WAIT_L(n) asm volatile("s_waitcnt lgkmcnt(" #n ")" ::: "memory")
; #define PG8_BAR __builtin_amdgcn_s_barrier()
; template <class Epi, class Sched, bool ALIGN_EPI = false, bool SP2 = false>
; __device__ __forceinline__ void gemm_phase(PG8_LAS unsigned char* lds, const Gemm g, const Sched& S, const Epi& E, int tid_in) {
;     ...
;         for (int t = 0; t < nt; t += 2) {
;             const bool last = (t == nt - 2);
;             const char* a1 = cA + (size_t)(t + 1) * kstep;
;             const char* a2 = last ? nA : cA + (size_t)(t + 2) * kstep; const char* b2 = last ? nB : cB + (size_t)(t + 2) * kstep;
;             const char* a3 = a2 + kstep; const char* b3 = b2 + kstep;
;             if (last && has_next) S.a_ready(nxt);
;             if constexpr (SP2) {
;             PG8_LDB(B0, 0, 0); PG8_LDB(B1, 0, 1); PG8_SCHED; PG8_LDA(At, 0, 0); PG8_STAGE(PG8_SA(1, 1), a1 + hstep, voffA);
;             PG8_WAIT_V(8); PG8_WAIT_L(0); PG8_BAR; PG8_MMA(0, 0, At, B0); PG8_MMA(0, 1, At, B1); PG8_BAR; PG8_SCHED;
;             PG8_LDA(At, 0, 1); PG8_STAGE(PG8_SB(0, 0), b2, voffB); PG8_STAGE(PG8_SB(0, 1), b2 + hstep, voffB); PG8_STAGE(PG8_SA(0, 0), a2, voffA);
;             PG8_WAIT_V(8); PG8_WAIT_L(0); PG8_BAR; PG8_MMA(1, 0, At, B0); PG8_MMA(1, 1, At, B1); PG8_BAR; PG8_SCHED;
;             PG8_LDB(B0, 1, 0); PG8_LDB(B1, 1, 1); PG8_SCHED; PG8_LDA(At, 1, 0); PG8_STAGE(PG8_SA(0, 1), a2 + hstep, voffA);
;             PG8_WAIT_V(8); PG8_WAIT_L(0); PG8_BAR; PG8_MMA(0, 0, At, B0); PG8_MMA(0, 1, At, B1); PG8_BAR; PG8_SCHED;
;             PG8_LDA(At, 1, 1); PG8_STAGE(PG8_SB(1, 0), b3, voffB); PG8_STAGE(PG8_SB(1, 1), b3 + hstep, voffB); PG8_STAGE(PG8_SA(1, 0), a3, voffA);
;             PG8_WAIT_V(8); PG8_WAIT_L(0); PG8_BAR; PG8_MMA(1, 0, At, B0); PG8_MMA(1, 1, At, B1); PG8_BAR; PG8_SCHED;
	s_add_i32 s28, s51, s36
	v_lshl_add_u64 v[192:193], v[192:193], 0, s[84:85]
	s_mov_b32 m0, s28
	ds_read_b128 v[162:165], v219 offset:49152
	ds_read_b128 v[166:169], v219 offset:50176
	ds_read_b128 v[170:173], v219 offset:51200
	ds_read_b128 v[174:177], v219 offset:52224
	ds_read_b128 v[188:191], v219 offset:53248
	ds_read_b128 v[204:207], v219 offset:54272
	ds_read_b128 v[208:211], v219 offset:55296
	ds_read_b128 v[212:215], v219 offset:56320
	global_load_lds_dwordx4 v[192:193], off
	s_add_i32 m0, s28, 0x2000
	s_add_u32 s26, s26, 0x40080
	v_lshl_add_u64 v[192:193], v[220:221], 0, s[84:85]
	s_addc_u32 s27, s27, 0
	s_add_i32 s28, s52, s36
	global_load_lds_dwordx4 v[192:193], off
	s_mov_b32 m0, s28
	s_nop 0
	global_load_lds_dwordx4 v32, s[26:27]
	s_add_i32 m0, s28, 0x2000
	s_nop 0
	global_load_lds_dwordx4 v178, s[26:27]
	v_lshl_add_u64 v[192:193], v[222:223], 0, s[84:85]
	s_mov_b32 m0, s41
	s_nop 0
	global_load_lds_dwordx4 v[192:193], off
	v_lshl_add_u64 v[192:193], v[224:225], 0, s[84:85]
	s_mov_b32 m0, s42
	s_nop 0
	global_load_lds_dwordx4 v[192:193], off
	s_waitcnt vmcnt(8)
	s_waitcnt lgkmcnt(0)
	s_barrier
	s_setprio 1
	s_waitcnt lgkmcnt(0)
	v_mfma_f32_16x16x32_bf16 v[62:65], v[130:133], v[162:165], v[62:65]
	v_mfma_f32_16x16x32_bf16 v[58:61], v[138:141], v[162:165], v[58:61]
	v_mfma_f32_16x16x32_bf16 v[46:49], v[130:133], v[170:173], v[46:49]
	v_mfma_f32_16x16x32_bf16 v[42:45], v[138:141], v[170:173], v[42:45]
	v_mfma_f32_16x16x32_bf16 v[28:31], v[130:133], v[188:191], v[28:31]
	v_mfma_f32_16x16x32_bf16 v[24:27], v[138:141], v[188:191], v[24:27]
	v_mfma_f32_16x16x32_bf16 v[12:15], v[130:133], v[208:211], v[12:15]
	v_mfma_f32_16x16x32_bf16 v[8:11], v[138:141], v[208:211], v[8:11]
	v_mfma_f32_16x16x32_bf16 v[62:65], v[134:137], v[166:169], v[62:65]
	v_mfma_f32_16x16x32_bf16 v[58:61], v[142:145], v[166:169], v[58:61]
	v_mfma_f32_16x16x32_bf16 v[46:49], v[134:137], v[174:177], v[46:49]
	v_mfma_f32_16x16x32_bf16 v[42:45], v[142:145], v[174:177], v[42:45]
	v_mfma_f32_16x16x32_bf16 v[28:31], v[134:137], v[204:207], v[28:31]
	v_mfma_f32_16x16x32_bf16 v[24:27], v[142:145], v[204:207], v[24:27]
	v_mfma_f32_16x16x32_bf16 v[12:15], v[134:137], v[212:215], v[12:15]
	v_mfma_f32_16x16x32_bf16 v[8:11], v[142:145], v[212:215], v[8:11]
	s_setprio 0
	s_setprio 1
	v_mfma_f32_16x16x32_bf16 v[54:57], v[146:149], v[162:165], v[54:57]
	v_mfma_f32_16x16x32_bf16 v[50:53], v[154:157], v[162:165], v[50:53]
	v_mfma_f32_16x16x32_bf16 v[38:41], v[146:149], v[170:173], v[38:41]
	v_mfma_f32_16x16x32_bf16 v[34:37], v[154:157], v[170:173], v[34:37]
	v_mfma_f32_16x16x32_bf16 v[20:23], v[146:149], v[188:191], v[20:23]
	v_mfma_f32_16x16x32_bf16 v[16:19], v[154:157], v[188:191], v[16:19]
	v_mfma_f32_16x16x32_bf16 v[4:7], v[146:149], v[208:211], v[4:7]
	v_mfma_f32_16x16x32_bf16 v[0:3], v[154:157], v[208:211], v[0:3]
	v_mfma_f32_16x16x32_bf16 v[54:57], v[150:153], v[166:169], v[54:57]
	v_mfma_f32_16x16x32_bf16 v[50:53], v[158:161], v[166:169], v[50:53]
	v_mfma_f32_16x16x32_bf16 v[38:41], v[150:153], v[174:177], v[38:41]
	v_mfma_f32_16x16x32_bf16 v[34:37], v[158:161], v[174:177], v[34:37]
	v_mfma_f32_16x16x32_bf16 v[20:23], v[150:153], v[204:207], v[20:23]
	v_mfma_f32_16x16x32_bf16 v[16:19], v[158:161], v[204:207], v[16:19]
	v_mfma_f32_16x16x32_bf16 v[4:7], v[150:153], v[212:215], v[4:7]
	v_mfma_f32_16x16x32_bf16 v[0:3], v[158:161], v[212:215], v[0:3]
	s_setprio 0
	s_barrier
	s_add_i32 s50, s50, 2
	s_add_u32 s2, s2, 0x100
	s_addc_u32 s3, s3, 0
	s_add_u32 s48, s48, 0x100
	s_addc_u32 s49, s49, 0
	s_cmp_gt_u32 s50, 13
	s_cbranch_scc0 .LBB0_920
	s_and_b64 vcc, exec, s[16:17]
	s_cbranch_vccz .LBB0_923
	s_barrier

; #define PG8_STAGE(bufoff, gbase, voff) do { _Pragma("unroll") for (int _i = 0; _i < 2; ++_i) \
;         __builtin_amdgcn_global_load_lds((const unsigned*)((const char*)(gbase) + (voff)[_i]), (PG8_LAS unsigned*)(lds + (bufoff) + ldsw + _i * 8192), 16, 0, 0); } while (0)
; #define PG8_LDA(dst, b, h) do { _Pragma("unroll") for (int m = 0; m < 4; ++m) _Pragma("unroll") for (int k = 0; k < 2; ++k) dst[m][k] = *(const PG8_LAS bf16x8*)(lds + PG8_SA(b, h) + aoff + m * 2048 + k * 1024); } while (0)
; #define PG8_LDB(dst, b, h) do { _Pragma("unroll") for (int n = 0; n < 2; ++n) _Pragma("unroll") for (int k = 0; k < 2; ++k) dst[n][k] = *(const PG8_LAS bf16x8*)(lds + PG8_SB(b, h) + boff + n * 2048 + k * 1024); } while (0)
; #define PG8_MMA(ai, bj, At, Bt) do { __builtin_amdgcn_s_setprio(1); _Pragma("unroll") for (int m = 0; m < 4; ++m) _Pragma("unroll") for (int n = 0; n < 2; ++n) _Pragma("unroll") for (int k = 0; k < 2; ++k) \
;         acc[ai][bj][m][n] = __builtin_amdgcn_mfma_f32_16x16x32_bf16(Bt[n][k], At[m][k], acc[ai][bj][m][n], 0, 0, 0); __builtin_amdgcn_s_setprio(0); } while (0)
; #define PG8_WAIT_V(n) asm volatile("s_waitcnt vmcnt(" #n ")" ::: "memory")
; #define PG8_WAIT_L(n) asm volatile("s_waitcnt lgkmcnt(" #n ")" ::: "memory")
; #define PG8_BAR __builtin_amdgcn_s_barrier()
; #define PG8_SCHED __builtin_amdgcn_sched_barrier(0)
; template <class Epi, class Sched, bool ALIGN_EPI = false, bool SP2 = false>
; __device__ __forceinline__ void gemm_phase(PG8_LAS unsigned char* lds, const Gemm g, const Sched& S, const Epi& E, int tid_in) {
;     ...
;             PG8_LDB(B0, 0, 0); PG8_LDB(B1, 0, 1); PG8_SCHED; PG8_LDA(At, 0, 0); PG8_STAGE(PG8_SA(1, 1), a1 + hstep, voffA);
;             PG8_WAIT_V(8); PG8_WAIT_L(0); PG8_BAR; PG8_MMA(0, 0, At, B0); PG8_MMA(0, 1, At, B1); PG8_BAR; PG8_SCHED;
;             PG8_LDA(At, 0, 1); PG8_STAGE(PG8_SB(0, 0), b2, voffB); PG8_STAGE(PG8_SB(0, 1), b2 + hstep, voffB); PG8_STAGE(PG8_SA(0, 0), a2, voffA);
;             PG8_WAIT_V(8); PG8_WAIT_L(0); PG8_BAR; PG8_MMA(1, 0, At, B0); PG8_MMA(1, 1, At, B1); PG8_BAR; PG8_SCHED;
.LBB0_1010:
	s_add_u32 s6, s2, 0x100
	s_addc_u32 s7, s3, 0
	s_add_i32 s52, 0, 0x10000
	s_cmp_eq_u32 s51, 40
	s_cselect_b32 s29, s23, s7
	s_cselect_b32 s28, s22, s6
	s_cselect_b32 s27, s25, s50
	s_cselect_b32 s26, s24, s49
	s_add_i32 s53, 0, 0x14000
	v_add_u32_e32 v142, s52, v248
	v_add_u32_e32 v158, s53, v248
	ds_read_b128 v[130:133], v142
	ds_read_b128 v[134:137], v142 offset:1024
	ds_read_b128 v[138:141], v142 offset:2048
	ds_read_b128 v[142:145], v142 offset:3072
	ds_read_b128 v[146:149], v158
	ds_read_b128 v[150:153], v158 offset:1024
	ds_read_b128 v[154:157], v158 offset:2048
	ds_read_b128 v[158:161], v158 offset:3072
	v_lshl_add_u64 v[214:215], s[2:3], 0, v[210:211]
	s_add_i32 m0, s38, 0xc000
	ds_read_b128 v[162:165], v250
	ds_read_b128 v[166:169], v250 offset:1024
	ds_read_b128 v[170:173], v250 offset:2048
	ds_read_b128 v[174:177], v250 offset:3072
	ds_read_b128 v[178:181], v250 offset:4096
	ds_read_b128 v[182:185], v250 offset:5120
	ds_read_b128 v[186:189], v250 offset:6144
	ds_read_b128 v[190:193], v250 offset:7168
	global_load_lds_dwordx4 v[214:215], off
	v_lshl_add_u64 v[214:215], s[2:3], 0, v[212:213]
	s_add_i32 m0, s38, 0xe000
	s_nop 0
	global_load_lds_dwordx4 v[214:215], off
	s_waitcnt vmcnt(8)
	s_waitcnt lgkmcnt(0)
	s_barrier
	s_setprio 1
	s_waitcnt lgkmcnt(0)
	v_mfma_f32_16x16x32_bf16 v[126:129], v[130:133], v[162:165], v[126:129]
	v_mfma_f32_16x16x32_bf16 v[122:125], v[138:141], v[162:165], v[122:125]
	v_mfma_f32_16x16x32_bf16 v[114:117], v[130:133], v[170:173], v[114:117]
	v_mfma_f32_16x16x32_bf16 v[106:109], v[138:141], v[170:173], v[106:109]
	v_mfma_f32_16x16x32_bf16 v[98:101], v[130:133], v[178:181], v[98:101]
	v_mfma_f32_16x16x32_bf16 v[90:93], v[138:141], v[178:181], v[90:93]
	v_mfma_f32_16x16x32_bf16 v[82:85], v[130:133], v[186:189], v[82:85]
	v_mfma_f32_16x16x32_bf16 v[74:77], v[138:141], v[186:189], v[74:77]
	v_mfma_f32_16x16x32_bf16 v[126:129], v[134:137], v[166:169], v[126:129]
	v_mfma_f32_16x16x32_bf16 v[122:125], v[142:145], v[166:169], v[122:125]
	v_mfma_f32_16x16x32_bf16 v[114:117], v[134:137], v[174:177], v[114:117]
	v_mfma_f32_16x16x32_bf16 v[106:109], v[142:145], v[174:177], v[106:109]
	v_mfma_f32_16x16x32_bf16 v[98:101], v[134:137], v[182:185], v[98:101]
	v_mfma_f32_16x16x32_bf16 v[90:93], v[142:145], v[182:185], v[90:93]
	v_mfma_f32_16x16x32_bf16 v[82:85], v[134:137], v[190:193], v[82:85]
	v_mfma_f32_16x16x32_bf16 v[74:77], v[142:145], v[190:193], v[74:77]
	s_setprio 0
	s_setprio 1
	v_mfma_f32_16x16x32_bf16 v[118:121], v[146:149], v[162:165], v[118:121]
	v_mfma_f32_16x16x32_bf16 v[110:113], v[154:157], v[162:165], v[110:113]
	v_mfma_f32_16x16x32_bf16 v[102:105], v[146:149], v[170:173], v[102:105]
	v_mfma_f32_16x16x32_bf16 v[94:97], v[154:157], v[170:173], v[94:97]
	v_mfma_f32_16x16x32_bf16 v[86:89], v[146:149], v[178:181], v[86:89]
	v_mfma_f32_16x16x32_bf16 v[78:81], v[154:157], v[178:181], v[78:81]
	v_mfma_f32_16x16x32_bf16 v[70:73], v[146:149], v[186:189], v[70:73]
	v_mfma_f32_16x16x32_bf16 v[66:69], v[154:157], v[186:189], v[66:69]
	v_mfma_f32_16x16x32_bf16 v[118:121], v[150:153], v[166:169], v[118:121]
	v_mfma_f32_16x16x32_bf16 v[110:113], v[158:161], v[166:169], v[110:113]
	v_mfma_f32_16x16x32_bf16 v[102:105], v[150:153], v[174:177], v[102:105]
	v_mfma_f32_16x16x32_bf16 v[94:97], v[158:161], v[174:177], v[94:97]
	v_mfma_f32_16x16x32_bf16 v[86:89], v[150:153], v[182:185], v[86:89]
	v_mfma_f32_16x16x32_bf16 v[78:81], v[158:161], v[182:185], v[78:81]
	v_mfma_f32_16x16x32_bf16 v[70:73], v[150:153], v[190:193], v[70:73]
	v_mfma_f32_16x16x32_bf16 v[66:69], v[158:161], v[190:193], v[66:69]
	s_setprio 0
	s_barrier
	s_add_i32 s2, s52, s31
	v_lshl_add_u64 v[214:215], s[26:27], 0, v[32:33]
	s_mov_b32 m0, s2
	ds_read_b128 v[162:165], v250 offset:16384
	ds_read_b128 v[166:169], v250 offset:17408
	ds_read_b128 v[170:173], v250 offset:18432
	ds_read_b128 v[174:177], v250 offset:19456
	ds_read_b128 v[178:181], v250 offset:20480
	ds_read_b128 v[182:185], v250 offset:21504
	ds_read_b128 v[186:189], v250 offset:22528
	ds_read_b128 v[190:193], v250 offset:23552
	global_load_lds_dwordx4 v[214:215], off
	s_add_i32 m0, s2, 0x2000
	s_add_u32 s2, s26, 0xb0000
	v_lshl_add_u64 v[216:217], s[26:27], 0, v[204:205]
	s_addc_u32 s3, s27, 0
	s_add_i32 s52, s53, s31
	global_load_lds_dwordx4 v[216:217], off
	s_mov_b32 m0, s52
	v_lshl_add_u64 v[220:221], s[28:29], 0, v[206:207]
	global_load_lds_dwordx4 v32, s[2:3]
	s_add_i32 m0, s52, 0x2000
	s_nop 0
	global_load_lds_dwordx4 v204, s[2:3]
	v_lshl_add_u64 v[218:219], s[28:29], 0, v[208:209]
	s_mov_b32 m0, s38
	s_nop 0
	global_load_lds_dwordx4 v[218:219], off
	s_mov_b32 m0, s39
	s_nop 0
	global_load_lds_dwordx4 v[220:221], off
	s_waitcnt vmcnt(8)
	s_waitcnt lgkmcnt(0)
	s_barrier
; #define PG8_STAGE(bufoff, gbase, voff) do { _Pragma("unroll") for (int _i = 0; _i < 2; ++_i) \
;         __builtin_amdgcn_global_load_lds((const unsigned*)((const char*)(gbase) + (voff)[_i]), (PG8_LAS unsigned*)(lds + (bufoff) + ldsw + _i * 8192), 16, 0, 0); } while (0)
; #define PG8_LDA(dst, b, h) do { _Pragma("unroll") for (int m = 0; m < 4; ++m) _Pragma("unroll") for (int k = 0; k < 2; ++k) dst[m][k] = *(const PG8_LAS bf16x8*)(lds + PG8_SA(b, h) + aoff + m * 2048 + k * 1024); } while (0)
; #define PG8_LDB(dst, b, h) do { _Pragma("unroll") for (int n = 0; n < 2; ++n) _Pragma("unroll") for (int k = 0; k < 2; ++k) dst[n][k] = *(const PG8_LAS bf16x8*)(lds + PG8_SB(b, h) + boff + n * 2048 + k * 1024); } while (0)
; #define PG8_MMA(ai, bj, At, Bt) do { __builtin_amdgcn_s_setprio(1); _Pragma("unroll") for (int m = 0; m < 4; ++m) _Pragma("unroll") for (int n = 0; n < 2; ++n) _Pragma("unroll") for (int k = 0; k < 2; ++k) \
;         acc[ai][bj][m][n] = __builtin_amdgcn_mfma_f32_16x16x32_bf16(Bt[n][k], At[m][k], acc[ai][bj][m][n], 0, 0, 0); __builtin_amdgcn_s_setprio(0); } while (0)
; #define PG8_WAIT_V(n) asm volatile("s_waitcnt vmcnt(" #n ")" ::: "memory")
; #define PG8_WAIT_L(n) asm volatile("s_waitcnt lgkmcnt(" #n ")" ::: "memory")
; #define PG8_BAR __builtin_amdgcn_s_barrier()
; #define PG8_SCHED __builtin_amdgcn_sched_barrier(0)
; template <class Epi, class Sched, bool ALIGN_EPI = false, bool SP2 = false>
; __device__ __forceinline__ void gemm_phase(PG8_LAS unsigned char* lds, const Gemm g, const Sched& S, const Epi& E, int tid_in) {
;     ...
;             PG8_WAIT_V(8); PG8_WAIT_L(0); PG8_BAR; PG8_MMA(1, 0, At, B0); PG8_MMA(1, 1, At, B1); PG8_BAR; PG8_SCHED;
;             PG8_LDB(B0, 1, 0); PG8_LDB(B1, 1, 1); PG8_SCHED; PG8_LDA(At, 1, 0); PG8_STAGE(PG8_SA(0, 1), a2 + hstep, voffA);
;             PG8_WAIT_V(8); PG8_WAIT_L(0); PG8_BAR; PG8_MMA(0, 0, At, B0); PG8_MMA(0, 1, At, B1); PG8_BAR; PG8_SCHED;
	s_setprio 1
	s_waitcnt lgkmcnt(0)
	v_mfma_f32_16x16x32_bf16 v[62:65], v[130:133], v[162:165], v[62:65]
	v_mfma_f32_16x16x32_bf16 v[58:61], v[138:141], v[162:165], v[58:61]
	v_mfma_f32_16x16x32_bf16 v[50:53], v[130:133], v[170:173], v[50:53]
	v_mfma_f32_16x16x32_bf16 v[42:45], v[138:141], v[170:173], v[42:45]
	v_mfma_f32_16x16x32_bf16 v[34:37], v[130:133], v[178:181], v[34:37]
	v_mfma_f32_16x16x32_bf16 v[24:27], v[138:141], v[178:181], v[24:27]
	v_mfma_f32_16x16x32_bf16 v[16:19], v[130:133], v[186:189], v[16:19]
	v_mfma_f32_16x16x32_bf16 v[8:11], v[138:141], v[186:189], v[8:11]
	v_mfma_f32_16x16x32_bf16 v[62:65], v[134:137], v[166:169], v[62:65]
	v_mfma_f32_16x16x32_bf16 v[58:61], v[142:145], v[166:169], v[58:61]
	v_mfma_f32_16x16x32_bf16 v[50:53], v[134:137], v[174:177], v[50:53]
	v_mfma_f32_16x16x32_bf16 v[42:45], v[142:145], v[174:177], v[42:45]
	v_mfma_f32_16x16x32_bf16 v[34:37], v[134:137], v[182:185], v[34:37]
	v_mfma_f32_16x16x32_bf16 v[24:27], v[142:145], v[182:185], v[24:27]
	v_mfma_f32_16x16x32_bf16 v[16:19], v[134:137], v[190:193], v[16:19]
	v_mfma_f32_16x16x32_bf16 v[8:11], v[142:145], v[190:193], v[8:11]
	s_setprio 0
	s_setprio 1
	v_mfma_f32_16x16x32_bf16 v[54:57], v[146:149], v[162:165], v[54:57]
	v_mfma_f32_16x16x32_bf16 v[46:49], v[154:157], v[162:165], v[46:49]
	v_mfma_f32_16x16x32_bf16 v[38:41], v[146:149], v[170:173], v[38:41]
	v_mfma_f32_16x16x32_bf16 v[28:31], v[154:157], v[170:173], v[28:31]
	v_mfma_f32_16x16x32_bf16 v[20:23], v[146:149], v[178:181], v[20:23]
	v_mfma_f32_16x16x32_bf16 v[12:15], v[154:157], v[178:181], v[12:15]
	v_mfma_f32_16x16x32_bf16 v[4:7], v[146:149], v[186:189], v[4:7]
	v_mfma_f32_16x16x32_bf16 v[0:3], v[154:157], v[186:189], v[0:3]
	v_mfma_f32_16x16x32_bf16 v[54:57], v[150:153], v[166:169], v[54:57]
	v_mfma_f32_16x16x32_bf16 v[46:49], v[158:161], v[166:169], v[46:49]
	v_mfma_f32_16x16x32_bf16 v[38:41], v[150:153], v[174:177], v[38:41]
	v_mfma_f32_16x16x32_bf16 v[28:31], v[158:161], v[174:177], v[28:31]
	v_mfma_f32_16x16x32_bf16 v[20:23], v[150:153], v[182:185], v[20:23]
	v_mfma_f32_16x16x32_bf16 v[12:15], v[158:161], v[182:185], v[12:15]
	v_mfma_f32_16x16x32_bf16 v[4:7], v[150:153], v[190:193], v[4:7]
	v_mfma_f32_16x16x32_bf16 v[0:3], v[158:161], v[190:193], v[0:3]
	s_setprio 0
	s_barrier
	s_add_i32 s52, 0, 0x18000
	s_add_i32 s53, 0, 0x1c000
	v_add_u32_e32 v142, s52, v248
	v_add_u32_e32 v158, s53, v248
	ds_read_b128 v[130:133], v142
	ds_read_b128 v[134:137], v142 offset:1024
	ds_read_b128 v[138:141], v142 offset:2048
	ds_read_b128 v[142:145], v142 offset:3072
	ds_read_b128 v[146:149], v158
	ds_read_b128 v[150:153], v158 offset:1024
	ds_read_b128 v[154:157], v158 offset:2048
	ds_read_b128 v[158:161], v158 offset:3072
	s_add_u32 s2, s28, 0xb0000
	s_addc_u32 s3, s29, 0
	s_mov_b32 m0, s40
	ds_read_b128 v[162:165], v250 offset:32768
	ds_read_b128 v[166:169], v250 offset:33792
	ds_read_b128 v[170:173], v250 offset:34816
	ds_read_b128 v[174:177], v250 offset:35840
	ds_read_b128 v[178:181], v250 offset:36864
	ds_read_b128 v[182:185], v250 offset:37888
	ds_read_b128 v[186:189], v250 offset:38912
	ds_read_b128 v[190:193], v250 offset:39936
	global_load_lds_dwordx4 v208, s[2:3]
	s_mov_b32 m0, s41
	s_nop 0
	global_load_lds_dwordx4 v206, s[2:3]
	s_waitcnt vmcnt(8)
	s_waitcnt lgkmcnt(0)
	s_barrier
	s_setprio 1
	s_waitcnt lgkmcnt(0)
	v_mfma_f32_16x16x32_bf16 v[126:129], v[130:133], v[162:165], v[126:129]
	v_mfma_f32_16x16x32_bf16 v[122:125], v[138:141], v[162:165], v[122:125]
	v_mfma_f32_16x16x32_bf16 v[114:117], v[130:133], v[170:173], v[114:117]
	v_mfma_f32_16x16x32_bf16 v[106:109], v[138:141], v[170:173], v[106:109]
	v_mfma_f32_16x16x32_bf16 v[98:101], v[130:133], v[178:181], v[98:101]
	v_mfma_f32_16x16x32_bf16 v[90:93], v[138:141], v[178:181], v[90:93]
	v_mfma_f32_16x16x32_bf16 v[82:85], v[130:133], v[186:189], v[82:85]
	v_mfma_f32_16x16x32_bf16 v[74:77], v[138:141], v[186:189], v[74:77]
	v_mfma_f32_16x16x32_bf16 v[126:129], v[134:137], v[166:169], v[126:129]
	v_mfma_f32_16x16x32_bf16 v[122:125], v[142:145], v[166:169], v[122:125]
	v_mfma_f32_16x16x32_bf16 v[114:117], v[134:137], v[174:177], v[114:117]
	v_mfma_f32_16x16x32_bf16 v[106:109], v[142:145], v[174:177], v[106:109]
	v_mfma_f32_16x16x32_bf16 v[98:101], v[134:137], v[182:185], v[98:101]
	v_mfma_f32_16x16x32_bf16 v[90:93], v[142:145], v[182:185], v[90:93]
	v_mfma_f32_16x16x32_bf16 v[82:85], v[134:137], v[190:193], v[82:85]
	v_mfma_f32_16x16x32_bf16 v[74:77], v[142:145], v[190:193], v[74:77]
	s_setprio 0
	s_setprio 1
	v_mfma_f32_16x16x32_bf16 v[118:121], v[146:149], v[162:165], v[118:121]
	v_mfma_f32_16x16x32_bf16 v[110:113], v[154:157], v[162:165], v[110:113]
	v_mfma_f32_16x16x32_bf16 v[102:105], v[146:149], v[170:173], v[102:105]
	v_mfma_f32_16x16x32_bf16 v[94:97], v[154:157], v[170:173], v[94:97]
	v_mfma_f32_16x16x32_bf16 v[86:89], v[146:149], v[178:181], v[86:89]
	v_mfma_f32_16x16x32_bf16 v[78:81], v[154:157], v[178:181], v[78:81]
	v_mfma_f32_16x16x32_bf16 v[70:73], v[146:149], v[186:189], v[70:73]
	v_mfma_f32_16x16x32_bf16 v[66:69], v[154:157], v[186:189], v[66:69]
	v_mfma_f32_16x16x32_bf16 v[118:121], v[150:153], v[166:169], v[118:121]
	v_mfma_f32_16x16x32_bf16 v[110:113], v[158:161], v[166:169], v[110:113]
	v_mfma_f32_16x16x32_bf16 v[102:105], v[150:153], v[174:177], v[102:105]
	v_mfma_f32_16x16x32_bf16 v[94:97], v[158:161], v[174:177], v[94:97]
	v_mfma_f32_16x16x32_bf16 v[86:89], v[150:153], v[182:185], v[86:89]
	v_mfma_f32_16x16x32_bf16 v[78:81], v[158:161], v[182:185], v[78:81]
	v_mfma_f32_16x16x32_bf16 v[70:73], v[150:153], v[190:193], v[70:73]
	v_mfma_f32_16x16x32_bf16 v[66:69], v[158:161], v[190:193], v[66:69]
	s_setprio 0
	s_barrier
; #define PG8_STAGE(bufoff, gbase, voff) do { _Pragma("unroll") for (int _i = 0; _i < 2; ++_i) \
;         __builtin_amdgcn_global_load_lds((const unsigned*)((const char*)(gbase) + (voff)[_i]), (PG8_LAS unsigned*)(lds + (bufoff) + ldsw + _i * 8192), 16, 0, 0); } while (0)
; #define PG8_LDA(dst, b, h) do { _Pragma("unroll") for (int m = 0; m < 4; ++m) _Pragma("unroll") for (int k = 0; k < 2; ++k) dst[m][k] = *(const PG8_LAS bf16x8*)(lds + PG8_SA(b, h) + aoff + m * 2048 + k * 1024); } while (0)
; #define PG8_WAIT_V(n) asm volatile("s_waitcnt vmcnt(" #n ")" ::: "memory")
; #define PG8_WAIT_L(n) asm volatile("s_waitcnt lgkmcnt(" #n ")" ::: "memory")
; #define PG8_BAR __builtin_amdgcn_s_barrier()
; template <class Epi, class Sched, bool ALIGN_EPI = false, bool SP2 = false>
; __device__ __forceinline__ void gemm_phase(PG8_LAS unsigned char* lds, const Gemm g, const Sched& S, const Epi& E, int tid_in) {
;     ...
;         for (int t = 0; t < nt; t += 2) {
;             const bool last = (t == nt - 2);
;             const char* a1 = cA + (size_t)(t + 1) * kstep;
;             const char* a2 = last ? nA : cA + (size_t)(t + 2) * kstep; const char* b2 = last ? nB : cB + (size_t)(t + 2) * kstep;
;             const char* a3 = a2 + kstep; const char* b3 = b2 + kstep;
;             if (last && has_next) S.a_ready(nxt);
;             if constexpr (SP2) {
;             PG8_LDB(B0, 0, 0); PG8_LDB(B1, 0, 1); PG8_SCHED; PG8_LDA(At, 0, 0); PG8_STAGE(PG8_SA(1, 1), a1 + hstep, voffA);
;             PG8_WAIT_V(8); PG8_WAIT_L(0); PG8_BAR; PG8_MMA(0, 0, At, B0); PG8_MMA(0, 1, At, B1); PG8_BAR; PG8_SCHED;
;             PG8_LDA(At, 0, 1); PG8_STAGE(PG8_SB(0, 0), b2, voffB); PG8_STAGE(PG8_SB(0, 1), b2 + hstep, voffB); PG8_STAGE(PG8_SA(0, 0), a2, voffA);
;             PG8_WAIT_V(8); PG8_WAIT_L(0); PG8_BAR; PG8_MMA(1, 0, At, B0); PG8_MMA(1, 1, At, B1); PG8_BAR; PG8_SCHED;
;             PG8_LDB(B0, 1, 0); PG8_LDB(B1, 1, 1); PG8_SCHED; PG8_LDA(At, 1, 0); PG8_STAGE(PG8_SA(0, 1), a2 + hstep, voffA);
;             PG8_WAIT_V(8); PG8_WAIT_L(0); PG8_BAR; PG8_MMA(0, 0, At, B0); PG8_MMA(0, 1, At, B1); PG8_BAR; PG8_SCHED;
;             PG8_LDA(At, 1, 1); PG8_STAGE(PG8_SB(1, 0), b3, voffB); PG8_STAGE(PG8_SB(1, 1), b3 + hstep, voffB); PG8_STAGE(PG8_SA(1, 0), a3, voffA);
;             PG8_WAIT_V(8); PG8_WAIT_L(0); PG8_BAR; PG8_MMA(1, 0, At, B0); PG8_MMA(1, 1, At, B1); PG8_BAR; PG8_SCHED;
	s_add_i32 s2, s52, s31
	v_lshl_add_u64 v[214:215], v[214:215], 0, s[84:85]
	s_mov_b32 m0, s2
	ds_read_b128 v[162:165], v250 offset:49152
	ds_read_b128 v[166:169], v250 offset:50176
	ds_read_b128 v[170:173], v250 offset:51200
	ds_read_b128 v[174:177], v250 offset:52224
	ds_read_b128 v[178:181], v250 offset:53248
	ds_read_b128 v[182:185], v250 offset:54272
	ds_read_b128 v[186:189], v250 offset:55296
	ds_read_b128 v[190:193], v250 offset:56320
	global_load_lds_dwordx4 v[214:215], off
	s_add_i32 m0, s2, 0x2000
	s_add_u32 s2, s26, 0xb0080
	v_lshl_add_u64 v[214:215], v[216:217], 0, s[84:85]
	s_addc_u32 s3, s27, 0
	s_add_i32 s26, s53, s31
	global_load_lds_dwordx4 v[214:215], off
	s_mov_b32 m0, s26
	s_nop 0
	global_load_lds_dwordx4 v32, s[2:3]
	s_add_i32 m0, s26, 0x2000
	s_nop 0
	global_load_lds_dwordx4 v204, s[2:3]
	v_lshl_add_u64 v[214:215], v[218:219], 0, s[84:85]
	s_mov_b32 m0, s42
	s_nop 0
	global_load_lds_dwordx4 v[214:215], off
	v_lshl_add_u64 v[214:215], v[220:221], 0, s[84:85]
	s_mov_b32 m0, s43
	s_nop 0
	global_load_lds_dwordx4 v[214:215], off
	s_waitcnt vmcnt(8)
	s_waitcnt lgkmcnt(0)
	s_barrier
	s_setprio 1
	s_waitcnt lgkmcnt(0)
	v_mfma_f32_16x16x32_bf16 v[62:65], v[130:133], v[162:165], v[62:65]
	v_mfma_f32_16x16x32_bf16 v[58:61], v[138:141], v[162:165], v[58:61]
	v_mfma_f32_16x16x32_bf16 v[50:53], v[130:133], v[170:173], v[50:53]
	v_mfma_f32_16x16x32_bf16 v[42:45], v[138:141], v[170:173], v[42:45]
	v_mfma_f32_16x16x32_bf16 v[34:37], v[130:133], v[178:181], v[34:37]
	v_mfma_f32_16x16x32_bf16 v[24:27], v[138:141], v[178:181], v[24:27]
	v_mfma_f32_16x16x32_bf16 v[16:19], v[130:133], v[186:189], v[16:19]
	v_mfma_f32_16x16x32_bf16 v[8:11], v[138:141], v[186:189], v[8:11]
	v_mfma_f32_16x16x32_bf16 v[62:65], v[134:137], v[166:169], v[62:65]
	v_mfma_f32_16x16x32_bf16 v[58:61], v[142:145], v[166:169], v[58:61]
	v_mfma_f32_16x16x32_bf16 v[50:53], v[134:137], v[174:177], v[50:53]
	v_mfma_f32_16x16x32_bf16 v[42:45], v[142:145], v[174:177], v[42:45]
	v_mfma_f32_16x16x32_bf16 v[34:37], v[134:137], v[182:185], v[34:37]
	v_mfma_f32_16x16x32_bf16 v[24:27], v[142:145], v[182:185], v[24:27]
	v_mfma_f32_16x16x32_bf16 v[16:19], v[134:137], v[190:193], v[16:19]
	v_mfma_f32_16x16x32_bf16 v[8:11], v[142:145], v[190:193], v[8:11]
	s_setprio 0
	s_setprio 1
	v_mfma_f32_16x16x32_bf16 v[54:57], v[146:149], v[162:165], v[54:57]
	v_mfma_f32_16x16x32_bf16 v[46:49], v[154:157], v[162:165], v[46:49]
	v_mfma_f32_16x16x32_bf16 v[38:41], v[146:149], v[170:173], v[38:41]
	v_mfma_f32_16x16x32_bf16 v[28:31], v[154:157], v[170:173], v[28:31]
	v_mfma_f32_16x16x32_bf16 v[20:23], v[146:149], v[178:181], v[20:23]
	v_mfma_f32_16x16x32_bf16 v[12:15], v[154:157], v[178:181], v[12:15]
	v_mfma_f32_16x16x32_bf16 v[4:7], v[146:149], v[186:189], v[4:7]
	v_mfma_f32_16x16x32_bf16 v[0:3], v[154:157], v[186:189], v[0:3]
	v_mfma_f32_16x16x32_bf16 v[54:57], v[150:153], v[166:169], v[54:57]
	v_mfma_f32_16x16x32_bf16 v[46:49], v[158:161], v[166:169], v[46:49]
	v_mfma_f32_16x16x32_bf16 v[38:41], v[150:153], v[174:177], v[38:41]
	v_mfma_f32_16x16x32_bf16 v[28:31], v[158:161], v[174:177], v[28:31]
	v_mfma_f32_16x16x32_bf16 v[20:23], v[150:153], v[182:185], v[20:23]
	v_mfma_f32_16x16x32_bf16 v[12:15], v[158:161], v[182:185], v[12:15]
	v_mfma_f32_16x16x32_bf16 v[4:7], v[150:153], v[190:193], v[4:7]
	v_mfma_f32_16x16x32_bf16 v[0:3], v[158:161], v[190:193], v[0:3]
	s_setprio 0
	s_barrier
	s_add_i32 s51, s51, 2
	s_add_u32 s49, s49, 0x100
	s_addc_u32 s50, s50, 0
	s_cmp_gt_u32 s51, 41
	s_mov_b64 s[2:3], s[6:7]
	s_cbranch_scc0 .LBB0_1010
	s_and_b64 vcc, exec, s[18:19]
	s_cbranch_vccz .LBB0_1013
	s_barrier
